# DSA q fragments and first key tiles requested during the second top-k pass; softmax mask by bfe+and; row sums accumulated under the PV MFMAs
# speedup vs baseline: 1.0567x; 1.0145x over previous
; #define GAS __attribute__((address_space(1)))
; __device__ __forceinline__ void indexer_unit(const Args& a, LAS unsigned char* lds, LAS unsigned long long* maskl, int b, int qblk, int wave, int lane) {
;     ...
;         if (n <= 256) {
;             const int lo = 64 * lane;
;             myword = (n >= lo + 64) ? ~0ull : (n > lo ? ((1ull << (n - lo)) - 1ull) : 0ull);
; __device__ __forceinline__ void dsa_unit32(const Args& a, LAS unsigned char* lds, const LAS unsigned long long* maskl, int b, int qb, int tid, int wave, int lane) {
;     ...
;     for (int ks = 0; ks < 8; ++ks) { const u32x4 w = __builtin_nontemporal_load((const GAS u32x4*)(z + (rowb + t0 + l31) * ZW + ZDQ + h * 128 + 16 * ks + 8 * hi)); qf[ks] = __builtin_bit_cast(bf16x8, w);
; #pragma unroll
;         for (int i = 0; i < 4; ++i) { const float x0 = bflo(w[i]), x1 = bfhi(w[i]); qs += x0 * x0 + x1 * x1; } }
;     qs += __shfl_xor(qs, 32);
;     const float negB = -1.01f * 11.313708498984761f * sqrtf(qs);
;     const int nkt = (t0 + 32 + 63) >> 6;
;     f32x16 O[4];
; #pragma unroll
;     for (int ct = 0; ct < 4; ++ct)
; #pragma unroll
;         for (int i = 0; i < 16; ++i) O[ct][i] = 0.f;
;     float l = 0.f;
;     u32x4 rk0[2], rv0[2], rk1[2], rv1[2];
;     const unsigned vok0 = (unsigned)((tid >> 4) * 128 + 8 * (tid & 15)) * 2u, vok1 = vok0 + 32u * 128u * 2u;
;     const unsigned vov0 = (unsigned)((tid >> 3) * SEQ + 8 * (tid & 7)) * 2u, vov1 = vov0 + 64u * (unsigned)SEQ * 2u;
;     const GAS char* ckb = (const GAS char*)ckv + (size_t)rowb * 256; const GAS char* cvb = (const GAS char*)ckvT + (size_t)b * 128 * SEQ * 2;
.LBB0_1101:
	s_xor_b64 s[0:1], s[0:1], -1
	v_writelane_b32 v254, s0, 48
	v_writelane_b32 v254, s1, 49
	s_cmp_eq_u32 s0, 0
	s_cbranch_scc1 .Ltk_nopf
	v_readlane_b32 s20, v254, 43
	v_readlane_b32 s21, v254, 46
	v_readlane_b32 s22, v254, 24
	v_readlane_b32 s23, v254, 25
	v_readlane_b32 s24, v254, 38
	v_readlane_b32 s25, v254, 45
	v_readlane_b32 s26, v254, 41
	v_readlane_b32 s27, v254, 42
	v_readlane_b32 s28, v254, 28
	v_readlane_b32 s29, v254, 29
	s_lshl_b32 s30, s20, 5
	s_add_i32 s21, s21, s30
	v_and_b32_e32 v68, 31, v252
	v_or_b32_e32 v68, s21, v68
	v_bfe_u32 v69, v252, 5, 1
	v_lshlrev_b32_e32 v70, 4, v69
	v_mov_b32_e32 v71, 0
	v_mov_b64_e32 v[72:73], s[22:23]
	s_movk_i32 s31, 0x1e00
	s_add_u32 s36, s24, 0x1000
	s_mov_b32 s37, 0
	v_mad_u64_u32 v[72:73], s[34:35], v68, s31, v[72:73]
	v_lshl_add_u64 v[72:73], v[72:73], 0, s[36:37]
	v_lshl_add_u64 v[72:73], v[72:73], 0, v[70:71]
	global_load_dwordx4 v[126:129], v[72:73], off nt
	global_load_dwordx4 v[0:3], v[72:73], off offset:32 nt
	global_load_dwordx4 v[118:121], v[72:73], off offset:64 nt
	global_load_dwordx4 v[122:125], v[72:73], off offset:96 nt
	global_load_dwordx4 v[130:133], v[72:73], off offset:128 nt
	global_load_dwordx4 v[134:137], v[72:73], off offset:160 nt
	global_load_dwordx4 v[138:141], v[72:73], off offset:192 nt
	global_load_dwordx4 v[142:145], v[72:73], off offset:224 nt
	v_lshlrev_b32_e32 v74, 4, v252
	v_add_u32_e32 v75, 0x2000, v74
	v_lshlrev_b32_e32 v76, 9, v252
	v_and_b32_e32 v77, 0x70, v74
	s_movk_i32 s38, 0xf000
	v_and_or_b32 v76, v76, s38, v77
	v_add_u32_e32 v78, 0x40000, v76
	s_lshl_b32 s39, s25, 19
	s_add_u32 s26, s26, s39
	s_addc_u32 s27, s27, 0
	s_add_u32 s28, s28, s39
	s_addc_u32 s29, s29, 0
	global_load_dwordx4 v[146:149], v74, s[26:27]
	global_load_dwordx4 v[150:153], v75, s[26:27]
	global_load_dwordx4 v[154:157], v76, s[28:29]
	global_load_dwordx4 v[158:161], v78, s[28:29]
	s_cmp_lt_u32 s30, 33
	s_cbranch_scc1 .Ltk_nopf
	s_add_u32 s26, s26, 0x4000
	s_addc_u32 s27, s27, 0
	global_load_dwordx4 v[162:165], v74, s[26:27]
	global_load_dwordx4 v[166:169], v75, s[26:27]
	global_load_dwordx4 v[170:173], v76, s[28:29] offset:128
	global_load_dwordx4 v[174:177], v78, s[28:29] offset:128
.Ltk_nopf:
	s_lshl_b32 s0, s8, 12
	s_add_i32 s0, s0, 0x21000
	v_lshl_add_u32 v66, v5, 3, s0
	v_lshl_add_u32 v97, v5, 2, 0
	v_or_b32_e32 v67, 63, v84
	v_mov_b32_e32 v96, v5
	v_cmp_gt_u32_e64 s[6:7], 32, v5
	s_mov_b32 s9, 0
	s_barrier
.Ltk_q:
	s_or_b32 s77, s9, s85
	s_add_i32 s88, s77, s76
	s_cmpk_gt_u32 s88, 0xff
	s_cbranch_scc1 .Ltk_full
	v_sub_co_u32_e32 v100, vcc, s88, v84
	v_add_u32_e32 v100, 1, v100
	v_lshlrev_b64 v[100:101], v100, -1
	v_not_b32_e32 v101, v101
	v_not_b32_e32 v100, v100
	v_cndmask_b32_e64 v100, v100, 0, vcc
	v_cndmask_b32_e64 v101, v101, 0, vcc
	v_cmp_lt_u32_e32 vcc, s88, v67
	s_nop 1
	v_cndmask_b32_e32 v101, -1, v101, vcc
	v_cndmask_b32_e32 v100, -1, v100, vcc
	s_branch .Ltk_store

; __device__ __forceinline__ void indexer_unit(const Args& a, LAS unsigned char* lds, LAS unsigned long long* maskl, int b, int qblk, int wave, int lane) {
;     ...
;             int need = 0; const unsigned long long lt = (1ull << lane) - 1ull;
;             if (!exact) {
;                 int cl = 0;
; #pragma unroll
;                 for (int r = 0; r < 32; ++r) cl += (u[r] > T) ? 1 : 0;
;                 int ngt = 0;
; #pragma unroll
;                 for (int bb = 0; bb < 6; ++bb) ngt += __popcll(__ballot((cl >> bb) & 1)) << bb;
;                 need = 256 - ngt;
;             }
; #pragma unroll
;             for (int g = 0; g < 8; ++g) if (4 * g < nr) {
; #pragma unroll
;                 for (int k = 0; k < 4; ++k) { const int r = 4 * g + k;
;                     unsigned ur = u[r]; asm volatile("" : "+v"(ur), "+v"(myword), "+s"(need));
;                     unsigned long long m;
;                     if (exact) m = __ballot(ur >= T);
;                     else { const unsigned long long eq = __ballot(ur == T), gt = __ballot(ur > T);
;                         const bool pick = (ur == T) && (__popcll(eq & lt) < need);
;                         m = gt | __ballot(pick); need -= __popcll(eq); if (need < 0) need = 0; }
;                     if (lane == r) myword = m; } }
.Ltk_nxt:
	s_add_i32 s11, s11, -1
	s_cmp_ge_i32 s11, 0
	s_cbranch_scc1 .Ltk_bit
	v_mov_b32_e32 v100, 0
	v_mov_b32_e32 v101, 0
	v_mov_b32_e32 v24, 0
	v_cmp_lt_u32_e64 s[24:25], s10, v32
	v_cmp_lt_u32_e64 s[26:27], s10, v33
	v_cmp_lt_u32_e64 s[28:29], s10, v34
	v_cmp_lt_u32_e64 s[30:31], s10, v35
	v_cmp_lt_u32_e64 s[34:35], s10, v36
	v_cmp_lt_u32_e64 s[36:37], s10, v37
	v_cmp_lt_u32_e64 s[38:39], s10, v38
	v_cmp_lt_u32_e64 s[40:41], s10, v39
	s_bcnt1_i32_b64 s42, s[24:25]
	s_bcnt1_i32_b64 s43, s[26:27]
	s_bcnt1_i32_b64 s44, s[28:29]
	s_bcnt1_i32_b64 s45, s[30:31]
	s_bcnt1_i32_b64 s46, s[34:35]
	s_bcnt1_i32_b64 s47, s[36:37]
	s_bcnt1_i32_b64 s48, s[38:39]
	s_bcnt1_i32_b64 s49, s[40:41]
	s_add_i32 s14, s42, s43
	v_add_u32_e32 v24, s44, v24
	v_add_u32_e32 v24, s45, v24
	v_add_u32_e32 v24, s46, v24
	v_add_u32_e32 v24, s47, v24
	v_add_u32_e32 v24, s48, v24
	v_add_u32_e32 v24, s49, v24
	s_cmp_lt_u32 s21, 2
	s_cbranch_scc1 .Ltk_tie_cnt_done
	v_cmp_lt_u32_e64 s[24:25], s10, v40
	v_cmp_lt_u32_e64 s[26:27], s10, v41
	v_cmp_lt_u32_e64 s[28:29], s10, v42
	v_cmp_lt_u32_e64 s[30:31], s10, v43
	v_cmp_lt_u32_e64 s[34:35], s10, v44
	v_cmp_lt_u32_e64 s[36:37], s10, v45
	v_cmp_lt_u32_e64 s[38:39], s10, v46
	v_cmp_lt_u32_e64 s[40:41], s10, v47
	s_bcnt1_i32_b64 s42, s[24:25]
	s_bcnt1_i32_b64 s43, s[26:27]
	s_bcnt1_i32_b64 s44, s[28:29]
	s_bcnt1_i32_b64 s45, s[30:31]
	s_bcnt1_i32_b64 s46, s[34:35]
	s_bcnt1_i32_b64 s47, s[36:37]
	s_bcnt1_i32_b64 s48, s[38:39]
	s_bcnt1_i32_b64 s49, s[40:41]
	s_add_i32 s14, s14, s42
	s_add_i32 s14, s14, s43
	v_add_u32_e32 v24, s44, v24
	v_add_u32_e32 v24, s45, v24
	v_add_u32_e32 v24, s46, v24
	v_add_u32_e32 v24, s47, v24
	v_add_u32_e32 v24, s48, v24
	v_add_u32_e32 v24, s49, v24
	s_cmp_lt_u32 s21, 3
	s_cbranch_scc1 .Ltk_tie_cnt_done
	v_cmp_lt_u32_e64 s[24:25], s10, v48
	v_cmp_lt_u32_e64 s[26:27], s10, v49
	v_cmp_lt_u32_e64 s[28:29], s10, v50
	v_cmp_lt_u32_e64 s[30:31], s10, v51
	v_cmp_lt_u32_e64 s[34:35], s10, v52
	v_cmp_lt_u32_e64 s[36:37], s10, v53
	v_cmp_lt_u32_e64 s[38:39], s10, v54
	v_cmp_lt_u32_e64 s[40:41], s10, v55
	s_bcnt1_i32_b64 s42, s[24:25]
	s_bcnt1_i32_b64 s43, s[26:27]
	s_bcnt1_i32_b64 s44, s[28:29]
	s_bcnt1_i32_b64 s45, s[30:31]
	s_bcnt1_i32_b64 s46, s[34:35]
	s_bcnt1_i32_b64 s47, s[36:37]
	s_bcnt1_i32_b64 s48, s[38:39]
	s_bcnt1_i32_b64 s49, s[40:41]
	s_add_i32 s14, s14, s42
	s_add_i32 s14, s14, s43
	v_add_u32_e32 v24, s44, v24
	v_add_u32_e32 v24, s45, v24
	v_add_u32_e32 v24, s46, v24
	v_add_u32_e32 v24, s47, v24
	v_add_u32_e32 v24, s48, v24
	v_add_u32_e32 v24, s49, v24
	s_cmp_lt_u32 s21, 4
	s_cbranch_scc1 .Ltk_tie_cnt_done
	v_cmp_lt_u32_e64 s[24:25], s10, v56
	v_cmp_lt_u32_e64 s[26:27], s10, v57
	v_cmp_lt_u32_e64 s[28:29], s10, v58
	v_cmp_lt_u32_e64 s[30:31], s10, v59
	v_cmp_lt_u32_e64 s[34:35], s10, v60
	v_cmp_lt_u32_e64 s[36:37], s10, v61
	v_cmp_lt_u32_e64 s[38:39], s10, v62
	v_cmp_lt_u32_e64 s[40:41], s10, v63
	s_bcnt1_i32_b64 s42, s[24:25]
	s_bcnt1_i32_b64 s43, s[26:27]
	s_bcnt1_i32_b64 s44, s[28:29]
	s_bcnt1_i32_b64 s45, s[30:31]
	s_bcnt1_i32_b64 s46, s[34:35]
	s_bcnt1_i32_b64 s47, s[36:37]
	s_bcnt1_i32_b64 s48, s[38:39]
	s_bcnt1_i32_b64 s49, s[40:41]
	s_add_i32 s14, s14, s42
	s_add_i32 s14, s14, s43
	v_add_u32_e32 v24, s44, v24
	v_add_u32_e32 v24, s45, v24
	v_add_u32_e32 v24, s46, v24
	v_add_u32_e32 v24, s47, v24
	v_add_u32_e32 v24, s48, v24
	v_add_u32_e32 v24, s49, v24
.Ltk_tie_cnt_done:
	s_nop 0
	v_readfirstlane_b32 s15, v24
	s_add_i32 s14, s14, s15
	s_sub_i32 s16, 0x100, s14
	v_cmp_eq_u32_e64 s[24:25], s10, v32
	v_cmp_lt_u32_e64 s[26:27], s10, v32
	s_bcnt1_i32_b64 s17, s[24:25]
	s_nop 0
	v_mbcnt_lo_u32_b32 v99, s24, 0
	v_mbcnt_hi_u32_b32 v99, s25, v99
	v_cmp_gt_u32_e64 s[28:29], s16, v99
	s_and_b64 s[28:29], s[28:29], s[24:25]
	s_or_b64 s[26:27], s[26:27], s[28:29]
	s_sub_i32 s16, s16, s17
	s_max_i32 s16, s16, 0
	v_writelane_b32 v100, s26, 0
	v_writelane_b32 v101, s27, 0
	v_cmp_eq_u32_e64 s[24:25], s10, v33
	v_cmp_lt_u32_e64 s[26:27], s10, v33
	s_bcnt1_i32_b64 s17, s[24:25]
	s_nop 0
	v_mbcnt_lo_u32_b32 v99, s24, 0
	v_mbcnt_hi_u32_b32 v99, s25, v99
	v_cmp_gt_u32_e64 s[28:29], s16, v99
	s_and_b64 s[28:29], s[28:29], s[24:25]
	s_or_b64 s[26:27], s[26:27], s[28:29]
	s_sub_i32 s16, s16, s17
	s_max_i32 s16, s16, 0
	v_writelane_b32 v100, s26, 1
	v_writelane_b32 v101, s27, 1
	v_cmp_eq_u32_e64 s[24:25], s10, v34
	v_cmp_lt_u32_e64 s[26:27], s10, v34
	s_bcnt1_i32_b64 s17, s[24:25]
	s_nop 0
	v_mbcnt_lo_u32_b32 v99, s24, 0
	v_mbcnt_hi_u32_b32 v99, s25, v99
	v_cmp_gt_u32_e64 s[28:29], s16, v99
	s_and_b64 s[28:29], s[28:29], s[24:25]
	s_or_b64 s[26:27], s[26:27], s[28:29]
	s_sub_i32 s16, s16, s17
	s_max_i32 s16, s16, 0
	v_writelane_b32 v100, s26, 2
	v_writelane_b32 v101, s27, 2
	v_cmp_eq_u32_e64 s[24:25], s10, v35
	v_cmp_lt_u32_e64 s[26:27], s10, v35
	s_bcnt1_i32_b64 s17, s[24:25]
	s_nop 0
	v_mbcnt_lo_u32_b32 v99, s24, 0
	v_mbcnt_hi_u32_b32 v99, s25, v99
	v_cmp_gt_u32_e64 s[28:29], s16, v99
	s_and_b64 s[28:29], s[28:29], s[24:25]
	s_or_b64 s[26:27], s[26:27], s[28:29]
	s_sub_i32 s16, s16, s17
	s_max_i32 s16, s16, 0
	v_writelane_b32 v100, s26, 3
	v_writelane_b32 v101, s27, 3
	v_cmp_eq_u32_e64 s[24:25], s10, v36
	v_cmp_lt_u32_e64 s[26:27], s10, v36
	s_bcnt1_i32_b64 s17, s[24:25]
	s_nop 0
	v_mbcnt_lo_u32_b32 v99, s24, 0
	v_mbcnt_hi_u32_b32 v99, s25, v99
	v_cmp_gt_u32_e64 s[28:29], s16, v99
	s_and_b64 s[28:29], s[28:29], s[24:25]
	s_or_b64 s[26:27], s[26:27], s[28:29]
	s_sub_i32 s16, s16, s17
	s_max_i32 s16, s16, 0
	v_writelane_b32 v100, s26, 4
	v_writelane_b32 v101, s27, 4
	v_cmp_eq_u32_e64 s[24:25], s10, v37
	v_cmp_lt_u32_e64 s[26:27], s10, v37
	s_bcnt1_i32_b64 s17, s[24:25]
	s_nop 0
	v_mbcnt_lo_u32_b32 v99, s24, 0
	v_mbcnt_hi_u32_b32 v99, s25, v99
	v_cmp_gt_u32_e64 s[28:29], s16, v99
	s_and_b64 s[28:29], s[28:29], s[24:25]
	s_or_b64 s[26:27], s[26:27], s[28:29]
	s_sub_i32 s16, s16, s17
	s_max_i32 s16, s16, 0
	v_writelane_b32 v100, s26, 5
	v_writelane_b32 v101, s27, 5
	v_cmp_eq_u32_e64 s[24:25], s10, v38
	v_cmp_lt_u32_e64 s[26:27], s10, v38
	s_bcnt1_i32_b64 s17, s[24:25]
	s_nop 0
	v_mbcnt_lo_u32_b32 v99, s24, 0
	v_mbcnt_hi_u32_b32 v99, s25, v99
	v_cmp_gt_u32_e64 s[28:29], s16, v99
	s_and_b64 s[28:29], s[28:29], s[24:25]
	s_or_b64 s[26:27], s[26:27], s[28:29]
	s_sub_i32 s16, s16, s17
	s_max_i32 s16, s16, 0
	v_writelane_b32 v100, s26, 6
	v_writelane_b32 v101, s27, 6
	v_cmp_eq_u32_e64 s[24:25], s10, v39
	v_cmp_lt_u32_e64 s[26:27], s10, v39
	s_bcnt1_i32_b64 s17, s[24:25]
	s_nop 0
	v_mbcnt_lo_u32_b32 v99, s24, 0
	v_mbcnt_hi_u32_b32 v99, s25, v99
	v_cmp_gt_u32_e64 s[28:29], s16, v99
	s_and_b64 s[28:29], s[28:29], s[24:25]
	s_or_b64 s[26:27], s[26:27], s[28:29]
	s_sub_i32 s16, s16, s17
	s_max_i32 s16, s16, 0
	v_writelane_b32 v100, s26, 7
	v_writelane_b32 v101, s27, 7
	s_cmp_lt_u32 s21, 2
	s_cbranch_scc1 .Ltk_store
; __device__ __forceinline__ void indexer_unit(const Args& a, LAS unsigned char* lds, LAS unsigned long long* maskl, int b, int qblk, int wave, int lane) {
;     ...
; #pragma unroll
;             for (int g = 0; g < 8; ++g) if (4 * g < nr) {
; #pragma unroll
;                 for (int k = 0; k < 4; ++k) { const int r = 4 * g + k;
;                     unsigned ur = u[r]; asm volatile("" : "+v"(ur), "+v"(myword), "+s"(need));
;                     unsigned long long m;
;                     if (exact) m = __ballot(ur >= T);
;                     else { const unsigned long long eq = __ballot(ur == T), gt = __ballot(ur > T);
;                         const bool pick = (ur == T) && (__popcll(eq & lt) < need);
;                         m = gt | __ballot(pick); need -= __popcll(eq); if (need < 0) need = 0; }
;                     if (lane == r) myword = m; } }
	v_cmp_eq_u32_e64 s[24:25], s10, v40
	v_cmp_lt_u32_e64 s[26:27], s10, v40
	s_bcnt1_i32_b64 s17, s[24:25]
	s_nop 0
	v_mbcnt_lo_u32_b32 v99, s24, 0
	v_mbcnt_hi_u32_b32 v99, s25, v99
	v_cmp_gt_u32_e64 s[28:29], s16, v99
	s_and_b64 s[28:29], s[28:29], s[24:25]
	s_or_b64 s[26:27], s[26:27], s[28:29]
	s_sub_i32 s16, s16, s17
	s_max_i32 s16, s16, 0
	v_writelane_b32 v100, s26, 8
	v_writelane_b32 v101, s27, 8
	v_cmp_eq_u32_e64 s[24:25], s10, v41
	v_cmp_lt_u32_e64 s[26:27], s10, v41
	s_bcnt1_i32_b64 s17, s[24:25]
	s_nop 0
	v_mbcnt_lo_u32_b32 v99, s24, 0
	v_mbcnt_hi_u32_b32 v99, s25, v99
	v_cmp_gt_u32_e64 s[28:29], s16, v99
	s_and_b64 s[28:29], s[28:29], s[24:25]
	s_or_b64 s[26:27], s[26:27], s[28:29]
	s_sub_i32 s16, s16, s17
	s_max_i32 s16, s16, 0
	v_writelane_b32 v100, s26, 9
	v_writelane_b32 v101, s27, 9
	v_cmp_eq_u32_e64 s[24:25], s10, v42
	v_cmp_lt_u32_e64 s[26:27], s10, v42
	s_bcnt1_i32_b64 s17, s[24:25]
	s_nop 0
	v_mbcnt_lo_u32_b32 v99, s24, 0
	v_mbcnt_hi_u32_b32 v99, s25, v99
	v_cmp_gt_u32_e64 s[28:29], s16, v99
	s_and_b64 s[28:29], s[28:29], s[24:25]
	s_or_b64 s[26:27], s[26:27], s[28:29]
	s_sub_i32 s16, s16, s17
	s_max_i32 s16, s16, 0
	v_writelane_b32 v100, s26, 10
	v_writelane_b32 v101, s27, 10
	v_cmp_eq_u32_e64 s[24:25], s10, v43
	v_cmp_lt_u32_e64 s[26:27], s10, v43
	s_bcnt1_i32_b64 s17, s[24:25]
	s_nop 0
	v_mbcnt_lo_u32_b32 v99, s24, 0
	v_mbcnt_hi_u32_b32 v99, s25, v99
	v_cmp_gt_u32_e64 s[28:29], s16, v99
	s_and_b64 s[28:29], s[28:29], s[24:25]
	s_or_b64 s[26:27], s[26:27], s[28:29]
	s_sub_i32 s16, s16, s17
	s_max_i32 s16, s16, 0
	v_writelane_b32 v100, s26, 11
	v_writelane_b32 v101, s27, 11
	v_cmp_eq_u32_e64 s[24:25], s10, v44
	v_cmp_lt_u32_e64 s[26:27], s10, v44
	s_bcnt1_i32_b64 s17, s[24:25]
	s_nop 0
	v_mbcnt_lo_u32_b32 v99, s24, 0
	v_mbcnt_hi_u32_b32 v99, s25, v99
	v_cmp_gt_u32_e64 s[28:29], s16, v99
	s_and_b64 s[28:29], s[28:29], s[24:25]
	s_or_b64 s[26:27], s[26:27], s[28:29]
	s_sub_i32 s16, s16, s17
	s_max_i32 s16, s16, 0
	v_writelane_b32 v100, s26, 12
	v_writelane_b32 v101, s27, 12
	v_cmp_eq_u32_e64 s[24:25], s10, v45
	v_cmp_lt_u32_e64 s[26:27], s10, v45
	s_bcnt1_i32_b64 s17, s[24:25]
	s_nop 0
	v_mbcnt_lo_u32_b32 v99, s24, 0
	v_mbcnt_hi_u32_b32 v99, s25, v99
	v_cmp_gt_u32_e64 s[28:29], s16, v99
	s_and_b64 s[28:29], s[28:29], s[24:25]
	s_or_b64 s[26:27], s[26:27], s[28:29]
	s_sub_i32 s16, s16, s17
	s_max_i32 s16, s16, 0
	v_writelane_b32 v100, s26, 13
	v_writelane_b32 v101, s27, 13
	v_cmp_eq_u32_e64 s[24:25], s10, v46
	v_cmp_lt_u32_e64 s[26:27], s10, v46
	s_bcnt1_i32_b64 s17, s[24:25]
	s_nop 0
	v_mbcnt_lo_u32_b32 v99, s24, 0
	v_mbcnt_hi_u32_b32 v99, s25, v99
	v_cmp_gt_u32_e64 s[28:29], s16, v99
	s_and_b64 s[28:29], s[28:29], s[24:25]
	s_or_b64 s[26:27], s[26:27], s[28:29]
	s_sub_i32 s16, s16, s17
	s_max_i32 s16, s16, 0
	v_writelane_b32 v100, s26, 14
	v_writelane_b32 v101, s27, 14
	v_cmp_eq_u32_e64 s[24:25], s10, v47
	v_cmp_lt_u32_e64 s[26:27], s10, v47
	s_bcnt1_i32_b64 s17, s[24:25]
	s_nop 0
	v_mbcnt_lo_u32_b32 v99, s24, 0
	v_mbcnt_hi_u32_b32 v99, s25, v99
	v_cmp_gt_u32_e64 s[28:29], s16, v99
	s_and_b64 s[28:29], s[28:29], s[24:25]
	s_or_b64 s[26:27], s[26:27], s[28:29]
	s_sub_i32 s16, s16, s17
	s_max_i32 s16, s16, 0
	v_writelane_b32 v100, s26, 15
	v_writelane_b32 v101, s27, 15
	s_cmp_lt_u32 s21, 3
	s_cbranch_scc1 .Ltk_store
	v_cmp_eq_u32_e64 s[24:25], s10, v48
	v_cmp_lt_u32_e64 s[26:27], s10, v48
	s_bcnt1_i32_b64 s17, s[24:25]
	s_nop 0
	v_mbcnt_lo_u32_b32 v99, s24, 0
	v_mbcnt_hi_u32_b32 v99, s25, v99
	v_cmp_gt_u32_e64 s[28:29], s16, v99
	s_and_b64 s[28:29], s[28:29], s[24:25]
	s_or_b64 s[26:27], s[26:27], s[28:29]
	s_sub_i32 s16, s16, s17
	s_max_i32 s16, s16, 0
	v_writelane_b32 v100, s26, 16
	v_writelane_b32 v101, s27, 16
	v_cmp_eq_u32_e64 s[24:25], s10, v49
	v_cmp_lt_u32_e64 s[26:27], s10, v49
	s_bcnt1_i32_b64 s17, s[24:25]
	s_nop 0
	v_mbcnt_lo_u32_b32 v99, s24, 0
	v_mbcnt_hi_u32_b32 v99, s25, v99
	v_cmp_gt_u32_e64 s[28:29], s16, v99
	s_and_b64 s[28:29], s[28:29], s[24:25]
	s_or_b64 s[26:27], s[26:27], s[28:29]
	s_sub_i32 s16, s16, s17
	s_max_i32 s16, s16, 0
	v_writelane_b32 v100, s26, 17
	v_writelane_b32 v101, s27, 17
	v_cmp_eq_u32_e64 s[24:25], s10, v50
	v_cmp_lt_u32_e64 s[26:27], s10, v50
	s_bcnt1_i32_b64 s17, s[24:25]
	s_nop 0
	v_mbcnt_lo_u32_b32 v99, s24, 0
	v_mbcnt_hi_u32_b32 v99, s25, v99
	v_cmp_gt_u32_e64 s[28:29], s16, v99
	s_and_b64 s[28:29], s[28:29], s[24:25]
	s_or_b64 s[26:27], s[26:27], s[28:29]
	s_sub_i32 s16, s16, s17
	s_max_i32 s16, s16, 0
	v_writelane_b32 v100, s26, 18
	v_writelane_b32 v101, s27, 18
	v_cmp_eq_u32_e64 s[24:25], s10, v51
	v_cmp_lt_u32_e64 s[26:27], s10, v51
	s_bcnt1_i32_b64 s17, s[24:25]
	s_nop 0
	v_mbcnt_lo_u32_b32 v99, s24, 0
	v_mbcnt_hi_u32_b32 v99, s25, v99
	v_cmp_gt_u32_e64 s[28:29], s16, v99
	s_and_b64 s[28:29], s[28:29], s[24:25]
	s_or_b64 s[26:27], s[26:27], s[28:29]
	s_sub_i32 s16, s16, s17
	s_max_i32 s16, s16, 0
	v_writelane_b32 v100, s26, 19
	v_writelane_b32 v101, s27, 19
	v_cmp_eq_u32_e64 s[24:25], s10, v52
	v_cmp_lt_u32_e64 s[26:27], s10, v52
	s_bcnt1_i32_b64 s17, s[24:25]
	s_nop 0
	v_mbcnt_lo_u32_b32 v99, s24, 0
	v_mbcnt_hi_u32_b32 v99, s25, v99
	v_cmp_gt_u32_e64 s[28:29], s16, v99
	s_and_b64 s[28:29], s[28:29], s[24:25]
	s_or_b64 s[26:27], s[26:27], s[28:29]
	s_sub_i32 s16, s16, s17
	s_max_i32 s16, s16, 0
	v_writelane_b32 v100, s26, 20
	v_writelane_b32 v101, s27, 20
	v_cmp_eq_u32_e64 s[24:25], s10, v53
	v_cmp_lt_u32_e64 s[26:27], s10, v53
	s_bcnt1_i32_b64 s17, s[24:25]
	s_nop 0
	v_mbcnt_lo_u32_b32 v99, s24, 0
	v_mbcnt_hi_u32_b32 v99, s25, v99
	v_cmp_gt_u32_e64 s[28:29], s16, v99
	s_and_b64 s[28:29], s[28:29], s[24:25]
	s_or_b64 s[26:27], s[26:27], s[28:29]
	s_sub_i32 s16, s16, s17
	s_max_i32 s16, s16, 0
	v_writelane_b32 v100, s26, 21
	v_writelane_b32 v101, s27, 21
	v_cmp_eq_u32_e64 s[24:25], s10, v54
	v_cmp_lt_u32_e64 s[26:27], s10, v54
	s_bcnt1_i32_b64 s17, s[24:25]
	s_nop 0
	v_mbcnt_lo_u32_b32 v99, s24, 0
	v_mbcnt_hi_u32_b32 v99, s25, v99
	v_cmp_gt_u32_e64 s[28:29], s16, v99
	s_and_b64 s[28:29], s[28:29], s[24:25]
	s_or_b64 s[26:27], s[26:27], s[28:29]
	s_sub_i32 s16, s16, s17
	s_max_i32 s16, s16, 0
	v_writelane_b32 v100, s26, 22
	v_writelane_b32 v101, s27, 22
	v_cmp_eq_u32_e64 s[24:25], s10, v55
	v_cmp_lt_u32_e64 s[26:27], s10, v55
	s_bcnt1_i32_b64 s17, s[24:25]
	s_nop 0
	v_mbcnt_lo_u32_b32 v99, s24, 0
	v_mbcnt_hi_u32_b32 v99, s25, v99
	v_cmp_gt_u32_e64 s[28:29], s16, v99
	s_and_b64 s[28:29], s[28:29], s[24:25]
	s_or_b64 s[26:27], s[26:27], s[28:29]
	s_sub_i32 s16, s16, s17
	s_max_i32 s16, s16, 0
	v_writelane_b32 v100, s26, 23
	v_writelane_b32 v101, s27, 23
	s_cmp_lt_u32 s21, 4
	s_cbranch_scc1 .Ltk_store
; __device__ __forceinline__ void indexer_unit(const Args& a, LAS unsigned char* lds, LAS unsigned long long* maskl, int b, int qblk, int wave, int lane) {
;     ...
; #pragma unroll
;             for (int g = 0; g < 8; ++g) if (4 * g < nr) {
; #pragma unroll
;                 for (int k = 0; k < 4; ++k) { const int r = 4 * g + k;
;                     unsigned ur = u[r]; asm volatile("" : "+v"(ur), "+v"(myword), "+s"(need));
;                     unsigned long long m;
;                     if (exact) m = __ballot(ur >= T);
;                     else { const unsigned long long eq = __ballot(ur == T), gt = __ballot(ur > T);
;                         const bool pick = (ur == T) && (__popcll(eq & lt) < need);
;                         m = gt | __ballot(pick); need -= __popcll(eq); if (need < 0) need = 0; }
;                     if (lane == r) myword = m; } }
	v_cmp_eq_u32_e64 s[24:25], s10, v56
	v_cmp_lt_u32_e64 s[26:27], s10, v56
	s_bcnt1_i32_b64 s17, s[24:25]
	s_nop 0
	v_mbcnt_lo_u32_b32 v99, s24, 0
	v_mbcnt_hi_u32_b32 v99, s25, v99
	v_cmp_gt_u32_e64 s[28:29], s16, v99
	s_and_b64 s[28:29], s[28:29], s[24:25]
	s_or_b64 s[26:27], s[26:27], s[28:29]
	s_sub_i32 s16, s16, s17
	s_max_i32 s16, s16, 0
	v_writelane_b32 v100, s26, 24
	v_writelane_b32 v101, s27, 24
	v_cmp_eq_u32_e64 s[24:25], s10, v57
	v_cmp_lt_u32_e64 s[26:27], s10, v57
	s_bcnt1_i32_b64 s17, s[24:25]
	s_nop 0
	v_mbcnt_lo_u32_b32 v99, s24, 0
	v_mbcnt_hi_u32_b32 v99, s25, v99
	v_cmp_gt_u32_e64 s[28:29], s16, v99
	s_and_b64 s[28:29], s[28:29], s[24:25]
	s_or_b64 s[26:27], s[26:27], s[28:29]
	s_sub_i32 s16, s16, s17
	s_max_i32 s16, s16, 0
	v_writelane_b32 v100, s26, 25
	v_writelane_b32 v101, s27, 25
	v_cmp_eq_u32_e64 s[24:25], s10, v58
	v_cmp_lt_u32_e64 s[26:27], s10, v58
	s_bcnt1_i32_b64 s17, s[24:25]
	s_nop 0
	v_mbcnt_lo_u32_b32 v99, s24, 0
	v_mbcnt_hi_u32_b32 v99, s25, v99
	v_cmp_gt_u32_e64 s[28:29], s16, v99
	s_and_b64 s[28:29], s[28:29], s[24:25]
	s_or_b64 s[26:27], s[26:27], s[28:29]
	s_sub_i32 s16, s16, s17
	s_max_i32 s16, s16, 0
	v_writelane_b32 v100, s26, 26
	v_writelane_b32 v101, s27, 26
	v_cmp_eq_u32_e64 s[24:25], s10, v59
	v_cmp_lt_u32_e64 s[26:27], s10, v59
	s_bcnt1_i32_b64 s17, s[24:25]
	s_nop 0
	v_mbcnt_lo_u32_b32 v99, s24, 0
	v_mbcnt_hi_u32_b32 v99, s25, v99
	v_cmp_gt_u32_e64 s[28:29], s16, v99
	s_and_b64 s[28:29], s[28:29], s[24:25]
	s_or_b64 s[26:27], s[26:27], s[28:29]
	s_sub_i32 s16, s16, s17
	s_max_i32 s16, s16, 0
	v_writelane_b32 v100, s26, 27
	v_writelane_b32 v101, s27, 27
	v_cmp_eq_u32_e64 s[24:25], s10, v60
	v_cmp_lt_u32_e64 s[26:27], s10, v60
	s_bcnt1_i32_b64 s17, s[24:25]
	s_nop 0
	v_mbcnt_lo_u32_b32 v99, s24, 0
	v_mbcnt_hi_u32_b32 v99, s25, v99
	v_cmp_gt_u32_e64 s[28:29], s16, v99
	s_and_b64 s[28:29], s[28:29], s[24:25]
	s_or_b64 s[26:27], s[26:27], s[28:29]
	s_sub_i32 s16, s16, s17
	s_max_i32 s16, s16, 0
	v_writelane_b32 v100, s26, 28
	v_writelane_b32 v101, s27, 28
	v_cmp_eq_u32_e64 s[24:25], s10, v61
	v_cmp_lt_u32_e64 s[26:27], s10, v61
	s_bcnt1_i32_b64 s17, s[24:25]
	s_nop 0
	v_mbcnt_lo_u32_b32 v99, s24, 0
	v_mbcnt_hi_u32_b32 v99, s25, v99
	v_cmp_gt_u32_e64 s[28:29], s16, v99
	s_and_b64 s[28:29], s[28:29], s[24:25]
	s_or_b64 s[26:27], s[26:27], s[28:29]
	s_sub_i32 s16, s16, s17
	s_max_i32 s16, s16, 0
	v_writelane_b32 v100, s26, 29
	v_writelane_b32 v101, s27, 29
	v_cmp_eq_u32_e64 s[24:25], s10, v62
	v_cmp_lt_u32_e64 s[26:27], s10, v62
	s_bcnt1_i32_b64 s17, s[24:25]
	s_nop 0
	v_mbcnt_lo_u32_b32 v99, s24, 0
	v_mbcnt_hi_u32_b32 v99, s25, v99
	v_cmp_gt_u32_e64 s[28:29], s16, v99
	s_and_b64 s[28:29], s[28:29], s[24:25]
	s_or_b64 s[26:27], s[26:27], s[28:29]
	s_sub_i32 s16, s16, s17
	s_max_i32 s16, s16, 0
	v_writelane_b32 v100, s26, 30
	v_writelane_b32 v101, s27, 30
	v_cmp_eq_u32_e64 s[24:25], s10, v63
	v_cmp_lt_u32_e64 s[26:27], s10, v63
	s_bcnt1_i32_b64 s17, s[24:25]
	s_nop 0
	v_mbcnt_lo_u32_b32 v99, s24, 0
	v_mbcnt_hi_u32_b32 v99, s25, v99
	v_cmp_gt_u32_e64 s[28:29], s16, v99
	s_and_b64 s[28:29], s[28:29], s[24:25]
	s_or_b64 s[26:27], s[26:27], s[28:29]
	s_sub_i32 s16, s16, s17
	s_max_i32 s16, s16, 0
	v_writelane_b32 v100, s26, 31
	v_writelane_b32 v101, s27, 31
	s_branch .Ltk_store
.Ltk_exact:
	v_mov_b32_e32 v100, 0
	v_mov_b32_e32 v101, 0
	v_cmp_le_u32_e64 s[24:25], s10, v32
	v_cmp_le_u32_e64 s[26:27], s10, v33
	v_cmp_le_u32_e64 s[28:29], s10, v34
	v_cmp_le_u32_e64 s[30:31], s10, v35
	v_cmp_le_u32_e64 s[34:35], s10, v36
	v_cmp_le_u32_e64 s[36:37], s10, v37
	v_cmp_le_u32_e64 s[38:39], s10, v38
	v_cmp_le_u32_e64 s[40:41], s10, v39
	v_writelane_b32 v100, s24, 0
	v_writelane_b32 v101, s25, 0
	v_writelane_b32 v100, s26, 1
	v_writelane_b32 v101, s27, 1
	v_writelane_b32 v100, s28, 2
	v_writelane_b32 v101, s29, 2
	v_writelane_b32 v100, s30, 3
	v_writelane_b32 v101, s31, 3
	v_writelane_b32 v100, s34, 4
	v_writelane_b32 v101, s35, 4
	v_writelane_b32 v100, s36, 5
	v_writelane_b32 v101, s37, 5
	v_writelane_b32 v100, s38, 6
	v_writelane_b32 v101, s39, 6
	v_writelane_b32 v100, s40, 7
	v_writelane_b32 v101, s41, 7
	s_cmp_lt_u32 s21, 2
	s_cbranch_scc1 .Ltk_store
	v_cmp_le_u32_e64 s[24:25], s10, v40
	v_cmp_le_u32_e64 s[26:27], s10, v41
	v_cmp_le_u32_e64 s[28:29], s10, v42
	v_cmp_le_u32_e64 s[30:31], s10, v43
	v_cmp_le_u32_e64 s[34:35], s10, v44
	v_cmp_le_u32_e64 s[36:37], s10, v45
	v_cmp_le_u32_e64 s[38:39], s10, v46
	v_cmp_le_u32_e64 s[40:41], s10, v47
	v_writelane_b32 v100, s24, 8
	v_writelane_b32 v101, s25, 8
	v_writelane_b32 v100, s26, 9
	v_writelane_b32 v101, s27, 9
	v_writelane_b32 v100, s28, 10
	v_writelane_b32 v101, s29, 10
	v_writelane_b32 v100, s30, 11
	v_writelane_b32 v101, s31, 11
	v_writelane_b32 v100, s34, 12
	v_writelane_b32 v101, s35, 12
	v_writelane_b32 v100, s36, 13
	v_writelane_b32 v101, s37, 13
	v_writelane_b32 v100, s38, 14
	v_writelane_b32 v101, s39, 14
	v_writelane_b32 v100, s40, 15
	v_writelane_b32 v101, s41, 15
	s_cmp_lt_u32 s21, 3
	s_cbranch_scc1 .Ltk_store
	v_cmp_le_u32_e64 s[24:25], s10, v48
	v_cmp_le_u32_e64 s[26:27], s10, v49
	v_cmp_le_u32_e64 s[28:29], s10, v50
	v_cmp_le_u32_e64 s[30:31], s10, v51
	v_cmp_le_u32_e64 s[34:35], s10, v52
	v_cmp_le_u32_e64 s[36:37], s10, v53
	v_cmp_le_u32_e64 s[38:39], s10, v54
	v_cmp_le_u32_e64 s[40:41], s10, v55
	v_writelane_b32 v100, s24, 16
	v_writelane_b32 v101, s25, 16
	v_writelane_b32 v100, s26, 17
	v_writelane_b32 v101, s27, 17
	v_writelane_b32 v100, s28, 18
	v_writelane_b32 v101, s29, 18
	v_writelane_b32 v100, s30, 19
	v_writelane_b32 v101, s31, 19
	v_writelane_b32 v100, s34, 20
	v_writelane_b32 v101, s35, 20
	v_writelane_b32 v100, s36, 21
	v_writelane_b32 v101, s37, 21
	v_writelane_b32 v100, s38, 22
	v_writelane_b32 v101, s39, 22
	v_writelane_b32 v100, s40, 23
	v_writelane_b32 v101, s41, 23
	s_cmp_lt_u32 s21, 4
	s_cbranch_scc1 .Ltk_store
	v_cmp_le_u32_e64 s[24:25], s10, v56
	v_cmp_le_u32_e64 s[26:27], s10, v57
	v_cmp_le_u32_e64 s[28:29], s10, v58
	v_cmp_le_u32_e64 s[30:31], s10, v59
	v_cmp_le_u32_e64 s[34:35], s10, v60
	v_cmp_le_u32_e64 s[36:37], s10, v61
	v_cmp_le_u32_e64 s[38:39], s10, v62
	v_cmp_le_u32_e64 s[40:41], s10, v63
	v_writelane_b32 v100, s24, 24
	v_writelane_b32 v101, s25, 24
	v_writelane_b32 v100, s26, 25
	v_writelane_b32 v101, s27, 25
	v_writelane_b32 v100, s28, 26
	v_writelane_b32 v101, s29, 26
	v_writelane_b32 v100, s30, 27
	v_writelane_b32 v101, s31, 27
	v_writelane_b32 v100, s34, 28
	v_writelane_b32 v101, s35, 28
	v_writelane_b32 v100, s36, 29
	v_writelane_b32 v101, s37, 29
	v_writelane_b32 v100, s38, 30
	v_writelane_b32 v101, s39, 30
	v_writelane_b32 v100, s40, 31
	v_writelane_b32 v101, s41, 31
; #define GAS __attribute__((address_space(1)))
; __device__ __forceinline__ void indexer_unit(const Args& a, LAS unsigned char* lds, LAS unsigned long long* maskl, int b, int qblk, int wave, int lane) {
;     ...
;                     if (lane == r) myword = m; } }
;         }
;         if (lane < 32) maskl[q * 32 + lane] = myword;
; __device__ __forceinline__ void dsa_unit32(const Args& a, LAS unsigned char* lds, const LAS unsigned long long* maskl, int b, int qb, int tid, int wave, int lane) {
;     ...
;     const int l31 = lane & 31, hi = lane >> 5, t0 = qb * 32, h = wave; const size_t rowb = (size_t)b * SEQ;
;     bf16x8 qf[8]; float qs = 0.f;
; #pragma unroll
;     for (int ks = 0; ks < 8; ++ks) { const u32x4 w = __builtin_nontemporal_load((const GAS u32x4*)(z + (rowb + t0 + l31) * ZW + ZDQ + h * 128 + 16 * ks + 8 * hi)); qf[ks] = __builtin_bit_cast(bf16x8, w);
; #pragma unroll
;         for (int i = 0; i < 4; ++i) { const float x0 = bflo(w[i]), x1 = bfhi(w[i]); qs += x0 * x0 + x1 * x1; } }
;     qs += __shfl_xor(qs, 32);
;     const float negB = -1.01f * 11.313708498984761f * sqrtf(qs);
;     const int nkt = (t0 + 32 + 63) >> 6;
;     f32x16 O[4];
; #pragma unroll
;     for (int ct = 0; ct < 4; ++ct)
; #pragma unroll
;         for (int i = 0; i < 16; ++i) O[ct][i] = 0.f;
;     float l = 0.f;
;     u32x4 rk0[2], rv0[2], rk1[2], rv1[2];
;     const unsigned vok0 = (unsigned)((tid >> 4) * 128 + 8 * (tid & 15)) * 2u, vok1 = vok0 + 32u * 128u * 2u;
;     const unsigned vov0 = (unsigned)((tid >> 3) * SEQ + 8 * (tid & 7)) * 2u, vov1 = vov0 + 64u * (unsigned)SEQ * 2u;
;     const GAS char* ckb = (const GAS char*)ckv + (size_t)rowb * 256; const GAS char* cvb = (const GAS char*)ckvT + (size_t)b * 128 * SEQ * 2;
.Ltk_store:
	s_and_saveexec_b64 s[0:1], s[6:7]
	v_lshl_add_u32 v99, s77, 8, v66
	ds_write_b64 v99, v[100:101]
	s_mov_b64 exec, s[0:1]
	s_add_i32 s9, s9, 1
	s_cmp_lt_u32 s9, 2
	s_cbranch_scc1 .Ltk_q
	s_branch .LBB0_1081
.LBB0_1298:
	v_readlane_b32 s0, v254, 43
	v_mov_b32_e32 v15, v252
	s_lshl_b32 s4, s0, 5
	v_readlane_b32 s0, v254, 46
	s_add_i32 s0, s0, s4
	v_and_b32_e32 v5, 31, v15
	v_or_b32_e32 v178, s0, v5
	v_readlane_b32 s0, v254, 24
	v_readlane_b32 s1, v254, 25
	v_bfe_u32 v14, v15, 5, 1
	v_lshlrev_b32_e32 v180, 4, v14
	s_movk_i32 s0, 0x1e00
	v_readlane_b32 s0, v254, 38
	v_readlane_b32 s1, v254, 39
	s_mov_b32 s1, s19
	v_mov_b32_e32 v181, v4
	s_mov_b32 s2, s0
	s_mov_b64 s[0:1], 0x1000
	v_writelane_b32 v254, s2, 38
	s_movk_i32 s0, 0xf000
	s_waitcnt vmcnt(0)
	v_and_b32_e32 v7, 0xffff0000, v0
	v_and_b32_e32 v33, 0xffff0000, v126
	v_and_b32_e32 v35, 0xffff0000, v127
	v_lshlrev_b32_e32 v32, 16, v126
	v_lshlrev_b32_e32 v34, 16, v127
	v_and_b32_e32 v37, 0xffff0000, v128
	v_mul_f32_e32 v33, v33, v33
	v_mul_f32_e32 v35, v35, v35
	v_lshlrev_b32_e32 v6, 16, v0
	v_lshlrev_b32_e32 v36, 16, v128
	v_and_b32_e32 v39, 0xffff0000, v129
	v_mul_f32_e32 v7, v7, v7
	v_mul_f32_e32 v37, v37, v37
	v_fmac_f32_e32 v33, v32, v32
	v_fmac_f32_e32 v35, v34, v34
	v_lshlrev_b32_e32 v38, 16, v129
	v_mul_f32_e32 v39, v39, v39
	v_fmac_f32_e32 v7, v6, v6
	v_fmac_f32_e32 v37, v36, v36
	v_add_f32_e32 v6, v33, v35
	v_and_b32_e32 v9, 0xffff0000, v1
	v_fmac_f32_e32 v39, v38, v38
	v_add_f32_e32 v6, v37, v6
	v_lshlrev_b32_e32 v8, 16, v1
	v_and_b32_e32 v11, 0xffff0000, v2
	v_mul_f32_e32 v9, v9, v9
	v_add_f32_e32 v6, v39, v6
	v_lshlrev_b32_e32 v10, 16, v2
	v_and_b32_e32 v13, 0xffff0000, v3
	v_mul_f32_e32 v11, v11, v11
	v_fmac_f32_e32 v9, v8, v8
	v_add_f32_e32 v6, v7, v6
	v_lshlrev_b32_e32 v12, 16, v3
	v_and_b32_e32 v17, 0xffff0000, v118
	v_mul_f32_e32 v13, v13, v13
	v_fmac_f32_e32 v11, v10, v10
	v_add_f32_e32 v6, v9, v6
	v_lshlrev_b32_e32 v16, 16, v118
	v_and_b32_e32 v19, 0xffff0000, v119
	v_mul_f32_e32 v17, v17, v17
	v_fmac_f32_e32 v13, v12, v12
	v_add_f32_e32 v6, v11, v6
	v_lshlrev_b32_e32 v18, 16, v119
	v_and_b32_e32 v21, 0xffff0000, v120
	v_mul_f32_e32 v19, v19, v19
	v_fmac_f32_e32 v17, v16, v16
	v_add_f32_e32 v6, v13, v6
	v_lshlrev_b32_e32 v20, 16, v120
	v_and_b32_e32 v23, 0xffff0000, v121
	v_mul_f32_e32 v21, v21, v21
	v_fmac_f32_e32 v19, v18, v18
	v_add_f32_e32 v6, v17, v6
	v_lshlrev_b32_e32 v22, 16, v121
	v_and_b32_e32 v25, 0xffff0000, v122
	v_mul_f32_e32 v23, v23, v23
	v_fmac_f32_e32 v21, v20, v20
	v_add_f32_e32 v6, v19, v6
	v_lshlrev_b32_e32 v24, 16, v122
	v_and_b32_e32 v27, 0xffff0000, v123
	v_mul_f32_e32 v25, v25, v25
	v_fmac_f32_e32 v23, v22, v22
	v_add_f32_e32 v6, v21, v6
	v_lshlrev_b32_e32 v26, 16, v123
	v_and_b32_e32 v29, 0xffff0000, v124
	v_mul_f32_e32 v27, v27, v27
	v_fmac_f32_e32 v25, v24, v24
	v_add_f32_e32 v6, v23, v6
	v_lshlrev_b32_e32 v28, 16, v124
	v_and_b32_e32 v31, 0xffff0000, v125
	v_mul_f32_e32 v29, v29, v29
	v_fmac_f32_e32 v27, v26, v26
	v_add_f32_e32 v6, v25, v6
	v_lshlrev_b32_e32 v30, 16, v125
	v_mul_f32_e32 v31, v31, v31
	v_fmac_f32_e32 v29, v28, v28
	v_add_f32_e32 v6, v27, v6
	v_and_b32_e32 v8, 0xffff0000, v130
	v_add_f32_e32 v6, v29, v6
	v_fmac_f32_e32 v31, v30, v30
	v_lshlrev_b32_e32 v7, 16, v130
	v_mul_f32_e32 v8, v8, v8
	v_add_f32_e32 v6, v31, v6
	v_fmac_f32_e32 v8, v7, v7
	v_add_f32_e32 v6, v8, v6
	v_and_b32_e32 v8, 0xffff0000, v131
	v_lshlrev_b32_e32 v7, 16, v131
	v_mul_f32_e32 v8, v8, v8
	v_fmac_f32_e32 v8, v7, v7
	v_add_f32_e32 v7, v8, v6
	v_lshlrev_b32_e32 v6, 4, v15
	v_writelane_b32 v254, s3, 39
	v_lshlrev_b32_e32 v10, 9, v15
	v_and_b32_e32 v16, 0x70, v6
	v_and_or_b32 v10, v10, s0, v16
	v_readlane_b32 s0, v254, 45
	s_lshl_b32 s18, s0, 19
	v_readlane_b32 s8, v254, 41
	v_readlane_b32 s9, v254, 42
	s_add_u32 s0, s8, s18
	s_addc_u32 s1, s9, 0
	v_readlane_b32 s2, v254, 28
	v_readlane_b32 s3, v254, 29
	s_add_u32 s2, s2, s18
	v_add_u32_e32 v8, 0x2000, v6
	v_add_u32_e32 v12, 0x40000, v10
	s_addc_u32 s3, s3, 0
	v_and_b32_e32 v11, 0xffff0000, v132
	v_lshlrev_b32_e32 v9, 16, v132
	v_mul_f32_e32 v11, v11, v11
	v_fmac_f32_e32 v11, v9, v9
	v_add_f32_e32 v7, v11, v7
	v_and_b32_e32 v11, 0xffff0000, v133
	v_lshlrev_b32_e32 v9, 16, v133
	v_mul_f32_e32 v11, v11, v11
	v_fmac_f32_e32 v11, v9, v9
	v_add_f32_e32 v7, v11, v7
	v_and_b32_e32 v11, 0xffff0000, v134
	v_lshlrev_b32_e32 v9, 16, v134
	v_mul_f32_e32 v11, v11, v11
	v_fmac_f32_e32 v11, v9, v9
	v_add_f32_e32 v7, v11, v7
	v_and_b32_e32 v11, 0xffff0000, v135
	v_lshlrev_b32_e32 v9, 16, v135
	v_mul_f32_e32 v11, v11, v11
	v_fmac_f32_e32 v11, v9, v9
	v_add_f32_e32 v7, v11, v7
	v_and_b32_e32 v11, 0xffff0000, v136
	v_lshlrev_b32_e32 v9, 16, v136
	v_mul_f32_e32 v11, v11, v11
	v_fmac_f32_e32 v11, v9, v9
	v_add_f32_e32 v7, v11, v7
	v_and_b32_e32 v11, 0xffff0000, v137
	v_lshlrev_b32_e32 v9, 16, v137
	v_mul_f32_e32 v11, v11, v11
	v_fmac_f32_e32 v11, v9, v9
	v_add_f32_e32 v7, v11, v7
	v_and_b32_e32 v11, 0xffff0000, v138
	v_lshlrev_b32_e32 v9, 16, v138
	v_mul_f32_e32 v11, v11, v11
	v_fmac_f32_e32 v11, v9, v9
	v_add_f32_e32 v7, v11, v7
	v_and_b32_e32 v11, 0xffff0000, v139
	v_lshlrev_b32_e32 v9, 16, v139
	v_mul_f32_e32 v11, v11, v11
	v_fmac_f32_e32 v11, v9, v9
	v_add_f32_e32 v7, v11, v7
	v_and_b32_e32 v11, 0xffff0000, v140
	v_lshlrev_b32_e32 v9, 16, v140
	v_mul_f32_e32 v11, v11, v11
	v_fmac_f32_e32 v11, v9, v9
	v_add_f32_e32 v7, v11, v7
	v_and_b32_e32 v11, 0xffff0000, v141
	v_lshlrev_b32_e32 v9, 16, v141
	v_mul_f32_e32 v11, v11, v11
	v_fmac_f32_e32 v11, v9, v9
	v_add_f32_e32 v7, v11, v7
	v_and_b32_e32 v11, 0xffff0000, v142
	v_lshlrev_b32_e32 v9, 16, v142
	v_mul_f32_e32 v11, v11, v11
	v_fmac_f32_e32 v11, v9, v9
	v_add_f32_e32 v7, v11, v7
	v_and_b32_e32 v11, 0xffff0000, v143
	v_lshlrev_b32_e32 v9, 16, v143
	v_mul_f32_e32 v11, v11, v11
	v_fmac_f32_e32 v11, v9, v9
	v_add_f32_e32 v7, v11, v7
	v_and_b32_e32 v11, 0xffff0000, v144
	v_lshlrev_b32_e32 v9, 16, v144
	v_mul_f32_e32 v11, v11, v11
	v_fmac_f32_e32 v11, v9, v9
	v_add_f32_e32 v7, v11, v7
	v_and_b32_e32 v11, 0xffff0000, v145
	v_lshlrev_b32_e32 v9, 16, v145
	v_mul_f32_e32 v11, v11, v11
	v_fmac_f32_e32 v11, v9, v9
	v_add_f32_e32 v17, v11, v7
	v_xor_b32_e32 v7, 32, v253
	v_cmp_lt_i32_e32 vcc, v7, v226
	v_mov_b32_e32 v9, v4
	v_mov_b32_e32 v11, v4
	v_cndmask_b32_e32 v7, v253, v7, vcc
	v_lshlrev_b32_e32 v181, 2, v7
	ds_bpermute_b32 v18, v181, v17
	v_mov_b32_e32 v7, v4
	s_cmp_lt_u32 s4, 33
	v_mov_b32_e32 v13, v4
	s_cbranch_scc1 .LBB0_1300
	s_add_u32 s0, s0, 0x4000
	s_addc_u32 s1, s1, 0
	v_lshl_add_u64 v[26:27], s[0:1], 0, v[6:7]
	v_lshl_add_u64 v[20:21], s[2:3], 0, v[10:11]
	v_lshl_add_u64 v[22:23], s[2:3], 0, v[12:13]
	v_lshl_add_u64 v[24:25], s[0:1], 0, v[8:9]

; #define DSA_GLOAD(kt, RK, RV) do { const GAS char* kb_ = ckb + (size_t)(kt) * (64 * 256); const GAS char* vb_ = cvb + (size_t)(kt) * 128; \
;         RK[0] = *(const GAS u32x4*)(kb_ + (size_t)vok0); RK[1] = *(const GAS u32x4*)(kb_ + (size_t)vok1); \
;         RV[0] = *(const GAS u32x4*)(vb_ + (size_t)vov0); RV[1] = *(const GAS u32x4*)(vb_ + (size_t)vov1); } while (0)
; __device__ __forceinline__ void dsa_unit32(const Args& a, LAS unsigned char* lds, const LAS unsigned long long* maskl, int b, int qb, int tid, int wave, int lane) {
;     ...
;     for (int kt = 0; kt < nkt; kt += 2) {
;         if (kt + 2 < nkt) DSA_GLOAD(kt + 2, rk0, rv0);
;         compute(0, kt);
;         if (kt + 1 < nkt) DSA_LSTORE(1, rk1, rv1);
;         __syncthreads();
;         if (kt + 1 >= nkt) break;
;         if (kt + 3 < nkt) DSA_GLOAD(kt + 3, rk1, rv1);
;         compute(1, kt + 1);
;         if (kt + 2 < nkt) DSA_LSTORE(0, rk0, rv0);
;         __syncthreads();
;     }
.LBB0_1301:
	s_mov_b64 s[0:1], 0x100
	s_add_i32 s5, s5, 2
	v_lshl_add_u64 v[186:187], v[186:187], 0, s[0:1]
	v_lshl_add_u64 v[188:189], v[188:189], 0, s[0:1]
	s_mov_b64 s[0:1], 0x8000
	s_cmp_ge_u32 s6, s4
	v_lshl_add_u64 v[190:191], v[190:191], 0, s[0:1]
	v_lshl_add_u64 v[192:193], v[192:193], 0, s[0:1]
	v_add_u32_e32 v206, 16, v206
	s_cselect_b64 s[2:3], -1, 0
	s_waitcnt lgkmcnt(0)
	s_barrier
	s_and_b64 vcc, exec, s[2:3]
	s_cbranch_vccnz .LBB0_1073

; #define LAS __attribute__((address_space(3)))
; __device__ __forceinline__ unsigned pk2(float lo, float hi) { f32x2_t v = {lo, hi}; bf16x2_t b = __builtin_convertvector(v, bf16x2_t); return __builtin_bit_cast(unsigned, b); }
; __device__ __forceinline__ void dsa_unit32(const Args& a, LAS unsigned char* lds, const LAS unsigned long long* maskl, int b, int qb, int tid, int wave, int lane) {
;     ...
;     auto compute = [&](int buf, int kt) {
;         const unsigned long long mw = maskl[l31 * 32 + kt];
;         const LAS bf16* Ks = (const LAS bf16*)(lds + buf * STG); const LAS bf16* Vs = (const LAS bf16*)(lds + buf * STG + KBYTES);
;         f32x16 S2[2];
; #pragma unroll
;         for (int kh = 0; kh < 2; ++kh) {
; #pragma unroll
;             for (int i = 0; i < 16; ++i) S2[kh][i] = negB;
;             __builtin_amdgcn_s_setprio(1);
; #pragma unroll
;             for (int ks = 0; ks < 8; ++ks) S2[kh] = mfma32(*(const LAS bf16x8*)(Ks + (32 * kh + l31) * KS + 16 * ks + 8 * hi), qf[ks], S2[kh]);
;             __builtin_amdgcn_s_setprio(0);
;         }
; #pragma unroll
;         for (int kh = 0; kh < 2; ++kh) {
;             const unsigned mh = (unsigned)(mw >> (32 * kh + 4 * hi));
;             float p[16];
; #pragma unroll
;             for (int i = 0; i < 16; ++i) { const float e = __builtin_amdgcn_exp2f(S2[kh][i]);
;                 const int keep = __builtin_amdgcn_sbfe((int)mh, 8 * (i >> 2) + (i & 3), 1);
;                 p[i] = __builtin_bit_cast(float, __builtin_bit_cast(int, e) & keep); l += p[i]; }
;             u32x4 w0, w1;
;             w0.x = pk2(p[0], p[1]); w0.y = pk2(p[2], p[3]); w0.z = pk2(p[4], p[5]); w0.w = pk2(p[6], p[7]);
;             w1.x = pk2(p[8], p[9]); w1.y = pk2(p[10], p[11]); w1.z = pk2(p[12], p[13]); w1.w = pk2(p[14], p[15]);
;             const bf16x8 pa = __builtin_bit_cast(bf16x8, w0), pb = __builtin_bit_cast(bf16x8, w1);
;             __builtin_amdgcn_s_setprio(1);
; #pragma unroll
;             for (int ct = 0; ct < 4; ++ct) {
;                 const LAS bf16* vr = Vs + (32 * ct + l31) * VS + 4 * hi + 32 * kh;
;                 O[ct] = mfma32(cat8(*(const LAS u32x2*)(vr), *(const LAS u32x2*)(vr + 8)), pa, O[ct]);
;                 O[ct] = mfma32(cat8(*(const LAS u32x2*)(vr + 16), *(const LAS u32x2*)(vr + 24)), pb, O[ct]);
;             }
;             __builtin_amdgcn_s_setprio(0);
;         }
.LBB0_1304:
	v_add_u32_e32 v207, -8, v206
	ds_read_b64 v[220:221], v207
	v_add_u32_e32 v207, v202, v180
	ds_read_b128 v[216:219], v207 offset:0
	ds_read_b128 v[228:231], v207 offset:32
	ds_read_b128 v[232:235], v207 offset:64
	ds_read_b128 v[236:239], v207 offset:96
	ds_read_b128 v[240:243], v207 offset:128
	ds_read_b128 v[244:247], v207 offset:160
	ds_read_b128 v[248:251], v207 offset:192
	ds_read_b128 v[222:225], v207 offset:224
	ds_read_b128 v[208:211], v207 offset:8704
	ds_read_b128 v[212:215], v207 offset:8736
	s_setprio 1
	s_waitcnt lgkmcnt(9)
	v_mfma_f32_32x32x16_bf16 v[102:117], v[216:219], v[126:129], v[70:85]
	ds_read_b128 v[216:219], v207 offset:8768
	s_waitcnt lgkmcnt(9)
	v_mfma_f32_32x32x16_bf16 v[102:117], v[228:231], v[0:3], v[102:117]
	ds_read_b128 v[228:231], v207 offset:8800
	s_waitcnt lgkmcnt(9)
	v_mfma_f32_32x32x16_bf16 v[102:117], v[232:235], v[118:121], v[102:117]
	ds_read_b128 v[232:235], v207 offset:8832
	s_waitcnt lgkmcnt(9)
	v_mfma_f32_32x32x16_bf16 v[102:117], v[236:239], v[122:125], v[102:117]
	ds_read_b128 v[236:239], v207 offset:8864
	s_waitcnt lgkmcnt(9)
	v_mfma_f32_32x32x16_bf16 v[102:117], v[240:243], v[130:133], v[102:117]
	ds_read_b128 v[240:243], v207 offset:8896
	s_waitcnt lgkmcnt(9)
	v_mfma_f32_32x32x16_bf16 v[102:117], v[244:247], v[134:137], v[102:117]
	ds_read_b128 v[244:247], v207 offset:8928
	s_waitcnt lgkmcnt(9)
	v_mfma_f32_32x32x16_bf16 v[102:117], v[248:251], v[138:141], v[102:117]
	s_waitcnt lgkmcnt(8)
	v_mfma_f32_32x32x16_bf16 v[102:117], v[222:225], v[142:145], v[102:117]
	s_waitcnt lgkmcnt(7)
	v_mfma_f32_32x32x16_bf16 v[86:101], v[208:211], v[126:129], v[70:85]
	s_waitcnt lgkmcnt(6)
	v_mfma_f32_32x32x16_bf16 v[86:101], v[212:215], v[0:3], v[86:101]
	s_waitcnt lgkmcnt(5)
	v_mfma_f32_32x32x16_bf16 v[86:101], v[216:219], v[118:121], v[86:101]
	v_add_u32_e32 v207, 17408, v203
	ds_read2_b64 v[248:251], v207 offset0:0 offset1:2
	ds_read2_b64 v[222:225], v207 offset0:4 offset1:6
	v_add_u32_e32 v207, 22272, v203
	ds_read2_b64 v[216:219], v207 offset0:0 offset1:2
	s_waitcnt lgkmcnt(7)
	v_mfma_f32_32x32x16_bf16 v[86:101], v[228:231], v[122:125], v[86:101]
	ds_read2_b64 v[228:231], v207 offset0:4 offset1:6
	s_waitcnt lgkmcnt(7)
	v_mfma_f32_32x32x16_bf16 v[86:101], v[232:235], v[130:133], v[86:101]
	v_add_u32_e32 v207, 27136, v203
	ds_read2_b64 v[232:235], v207 offset0:0 offset1:2
	s_waitcnt lgkmcnt(7)
	v_mfma_f32_32x32x16_bf16 v[86:101], v[236:239], v[134:137], v[86:101]
	ds_read2_b64 v[236:239], v207 offset0:4 offset1:6
	s_waitcnt lgkmcnt(7)
	v_mfma_f32_32x32x16_bf16 v[86:101], v[240:243], v[138:141], v[86:101]
	v_add_u32_e32 v207, 32000, v203
	ds_read2_b64 v[240:243], v207 offset0:0 offset1:2
	s_waitcnt lgkmcnt(7)
	v_mfma_f32_32x32x16_bf16 v[86:101], v[244:247], v[142:145], v[86:101]
	ds_read2_b64 v[244:247], v207 offset0:4 offset1:6
	s_setprio 0
	v_lshrrev_b64 v[208:209], v182, v[220:221]
	v_exp_f32_e32 v102, v102
	v_bfe_i32 v209, v208, 0, 1
	v_exp_f32_e32 v103, v103
	v_bfe_i32 v210, v208, 1, 1
	v_and_b32_e32 v102, v102, v209
	v_exp_f32_e32 v104, v104
	v_bfe_i32 v211, v208, 2, 1
	v_and_b32_e32 v103, v103, v210
	v_exp_f32_e32 v105, v105
	v_bfe_i32 v209, v208, 3, 1
	v_and_b32_e32 v104, v104, v211
	v_exp_f32_e32 v106, v106
	v_bfe_i32 v210, v208, 8, 1
	v_and_b32_e32 v105, v105, v209
	v_exp_f32_e32 v107, v107
	v_bfe_i32 v211, v208, 9, 1
	v_and_b32_e32 v106, v106, v210
	v_exp_f32_e32 v108, v108
	v_bfe_i32 v209, v208, 10, 1
	v_and_b32_e32 v107, v107, v211
	v_exp_f32_e32 v109, v109
	v_bfe_i32 v210, v208, 11, 1
	v_and_b32_e32 v108, v108, v209
	v_exp_f32_e32 v110, v110
	v_bfe_i32 v211, v208, 16, 1
	v_and_b32_e32 v109, v109, v210
	v_exp_f32_e32 v111, v111
	v_bfe_i32 v209, v208, 17, 1
	v_and_b32_e32 v110, v110, v211
	v_exp_f32_e32 v112, v112
	v_bfe_i32 v210, v208, 18, 1
	v_and_b32_e32 v111, v111, v209
	v_exp_f32_e32 v113, v113
	v_bfe_i32 v211, v208, 19, 1
	v_and_b32_e32 v112, v112, v210
	v_exp_f32_e32 v114, v114
	v_bfe_i32 v209, v208, 24, 1
	v_and_b32_e32 v113, v113, v211
	v_exp_f32_e32 v115, v115
	v_bfe_i32 v210, v208, 25, 1
	v_and_b32_e32 v114, v114, v209
	v_exp_f32_e32 v116, v116
	v_bfe_i32 v211, v208, 26, 1
	v_and_b32_e32 v115, v115, v210
	v_exp_f32_e32 v117, v117
	v_bfe_i32 v209, v208, 27, 1
	v_and_b32_e32 v116, v116, v211
	s_nop 0
	v_and_b32_e32 v117, v117, v209
	v_cvt_pk_bf16_f32 v208, v102, v103
	v_cvt_pk_bf16_f32 v209, v104, v105
	v_cvt_pk_bf16_f32 v210, v106, v107
	v_cvt_pk_bf16_f32 v211, v108, v109
	v_cvt_pk_bf16_f32 v212, v110, v111
	v_cvt_pk_bf16_f32 v213, v112, v113
	v_cvt_pk_bf16_f32 v214, v114, v115
	v_cvt_pk_bf16_f32 v215, v116, v117
	s_nop 1
	s_setprio 1
	s_waitcnt lgkmcnt(7)
	v_mfma_f32_32x32x16_bf16 v[54:69], v[248:251], v[208:211], v[54:69]
	v_add_u32_e32 v207, 17408, v203
	ds_read2_b64 v[248:251], v207 offset0:8 offset1:10
	v_add_f32_e32 v102, v194, v102
	v_add_f32_e32 v102, v103, v102
	s_waitcnt lgkmcnt(7)
	v_mfma_f32_32x32x16_bf16 v[54:69], v[222:225], v[212:215], v[54:69]
	ds_read2_b64 v[222:225], v207 offset0:12 offset1:14
	v_add_f32_e32 v102, v104, v102
	v_add_f32_e32 v102, v105, v102
	s_waitcnt lgkmcnt(7)
	v_mfma_f32_32x32x16_bf16 v[38:53], v[216:219], v[208:211], v[38:53]
	v_add_u32_e32 v207, 22272, v203
	ds_read2_b64 v[216:219], v207 offset0:8 offset1:10
	v_add_f32_e32 v102, v106, v102
	v_add_f32_e32 v102, v107, v102
	s_waitcnt lgkmcnt(7)
	v_mfma_f32_32x32x16_bf16 v[38:53], v[228:231], v[212:215], v[38:53]
	ds_read2_b64 v[228:231], v207 offset0:12 offset1:14
	v_add_f32_e32 v102, v108, v102
	v_add_f32_e32 v102, v109, v102
	s_waitcnt lgkmcnt(7)
	v_mfma_f32_32x32x16_bf16 v[22:37], v[232:235], v[208:211], v[22:37]
	v_add_u32_e32 v207, 27136, v203
	ds_read2_b64 v[232:235], v207 offset0:8 offset1:10
	v_add_f32_e32 v102, v110, v102
	v_add_f32_e32 v102, v111, v102
	s_waitcnt lgkmcnt(7)
; #define LAS __attribute__((address_space(3)))
; __device__ __forceinline__ unsigned pk2(float lo, float hi) { f32x2_t v = {lo, hi}; bf16x2_t b = __builtin_convertvector(v, bf16x2_t); return __builtin_bit_cast(unsigned, b); }
; __device__ __forceinline__ f32x16 mfma32(bf16x8 a, bf16x8 b, f32x16 c) { return __builtin_amdgcn_mfma_f32_32x32x16_bf16(a, b, c, 0, 0, 0); }
; __device__ __forceinline__ void dsa_unit32(const Args& a, LAS unsigned char* lds, const LAS unsigned long long* maskl, int b, int qb, int tid, int wave, int lane) {
;     ...
;         for (int kh = 0; kh < 2; ++kh) {
;             const unsigned mh = (unsigned)(mw >> (32 * kh + 4 * hi));
;             float p[16];
; #pragma unroll
;             for (int i = 0; i < 16; ++i) { const float e = __builtin_amdgcn_exp2f(S2[kh][i]);
;                 const int keep = __builtin_amdgcn_sbfe((int)mh, 8 * (i >> 2) + (i & 3), 1);
;                 p[i] = __builtin_bit_cast(float, __builtin_bit_cast(int, e) & keep); l += p[i]; }
;             u32x4 w0, w1;
;             w0.x = pk2(p[0], p[1]); w0.y = pk2(p[2], p[3]); w0.z = pk2(p[4], p[5]); w0.w = pk2(p[6], p[7]);
;             w1.x = pk2(p[8], p[9]); w1.y = pk2(p[10], p[11]); w1.z = pk2(p[12], p[13]); w1.w = pk2(p[14], p[15]);
;             const bf16x8 pa = __builtin_bit_cast(bf16x8, w0), pb = __builtin_bit_cast(bf16x8, w1);
;             __builtin_amdgcn_s_setprio(1);
; #pragma unroll
;             for (int ct = 0; ct < 4; ++ct) {
;                 const LAS bf16* vr = Vs + (32 * ct + l31) * VS + 4 * hi + 32 * kh;
;                 O[ct] = mfma32(cat8(*(const LAS u32x2*)(vr), *(const LAS u32x2*)(vr + 8)), pa, O[ct]);
;                 O[ct] = mfma32(cat8(*(const LAS u32x2*)(vr + 16), *(const LAS u32x2*)(vr + 24)), pb, O[ct]);
;             }
;             __builtin_amdgcn_s_setprio(0);
;         }
;     ...
;         if (kt + 2 < nkt) DSA_GLOAD(kt + 2, rk0, rv0);
;         compute(0, kt);
;         if (kt + 1 < nkt) DSA_LSTORE(1, rk1, rv1);
;         __syncthreads();
;         if (kt + 1 >= nkt) break;
;         if (kt + 3 < nkt) DSA_GLOAD(kt + 3, rk1, rv1);
;         compute(1, kt + 1);
;         if (kt + 2 < nkt) DSA_LSTORE(0, rk0, rv0);
	v_mfma_f32_32x32x16_bf16 v[22:37], v[236:239], v[212:215], v[22:37]
	ds_read2_b64 v[236:239], v207 offset0:12 offset1:14
	v_add_f32_e32 v102, v112, v102
	v_add_f32_e32 v102, v113, v102
	s_waitcnt lgkmcnt(7)
	v_mfma_f32_32x32x16_bf16 v[6:21], v[240:243], v[208:211], v[6:21]
	v_add_u32_e32 v207, 32000, v203
	ds_read2_b64 v[240:243], v207 offset0:8 offset1:10
	v_add_f32_e32 v102, v114, v102
	v_add_f32_e32 v102, v115, v102
	s_waitcnt lgkmcnt(7)
	v_mfma_f32_32x32x16_bf16 v[6:21], v[244:247], v[212:215], v[6:21]
	ds_read2_b64 v[244:247], v207 offset0:12 offset1:14
	v_add_f32_e32 v102, v116, v102
	v_add_f32_e32 v102, v117, v102
	s_setprio 0
	v_lshrrev_b64 v[208:209], v184, v[220:221]
	v_exp_f32_e32 v86, v86
	v_bfe_i32 v209, v208, 0, 1
	v_exp_f32_e32 v87, v87
	v_bfe_i32 v210, v208, 1, 1
	v_and_b32_e32 v86, v86, v209
	v_exp_f32_e32 v88, v88
	v_bfe_i32 v211, v208, 2, 1
	v_and_b32_e32 v87, v87, v210
	v_exp_f32_e32 v89, v89
	v_bfe_i32 v209, v208, 3, 1
	v_and_b32_e32 v88, v88, v211
	v_exp_f32_e32 v90, v90
	v_bfe_i32 v210, v208, 8, 1
	v_and_b32_e32 v89, v89, v209
	v_exp_f32_e32 v91, v91
	v_bfe_i32 v211, v208, 9, 1
	v_and_b32_e32 v90, v90, v210
	v_exp_f32_e32 v92, v92
	v_bfe_i32 v209, v208, 10, 1
	v_and_b32_e32 v91, v91, v211
	v_exp_f32_e32 v93, v93
	v_bfe_i32 v210, v208, 11, 1
	v_and_b32_e32 v92, v92, v209
	v_exp_f32_e32 v94, v94
	v_bfe_i32 v211, v208, 16, 1
	v_and_b32_e32 v93, v93, v210
	v_exp_f32_e32 v95, v95
	v_bfe_i32 v209, v208, 17, 1
	v_and_b32_e32 v94, v94, v211
	v_exp_f32_e32 v96, v96
	v_bfe_i32 v210, v208, 18, 1
	v_and_b32_e32 v95, v95, v209
	v_exp_f32_e32 v97, v97
	v_bfe_i32 v211, v208, 19, 1
	v_and_b32_e32 v96, v96, v210
	v_exp_f32_e32 v98, v98
	v_bfe_i32 v209, v208, 24, 1
	v_and_b32_e32 v97, v97, v211
	v_exp_f32_e32 v99, v99
	v_bfe_i32 v210, v208, 25, 1
	v_and_b32_e32 v98, v98, v209
	v_exp_f32_e32 v100, v100
	v_bfe_i32 v211, v208, 26, 1
	v_and_b32_e32 v99, v99, v210
	v_exp_f32_e32 v101, v101
	v_bfe_i32 v209, v208, 27, 1
	v_and_b32_e32 v100, v100, v211
	s_nop 0
	v_and_b32_e32 v101, v101, v209
	v_cvt_pk_bf16_f32 v208, v86, v87
	v_cvt_pk_bf16_f32 v209, v88, v89
	v_cvt_pk_bf16_f32 v210, v90, v91
	v_cvt_pk_bf16_f32 v211, v92, v93
	v_cvt_pk_bf16_f32 v212, v94, v95
	v_cvt_pk_bf16_f32 v213, v96, v97
	v_cvt_pk_bf16_f32 v214, v98, v99
	v_cvt_pk_bf16_f32 v215, v100, v101
	s_nop 1
	s_setprio 1
	s_waitcnt lgkmcnt(7)
	v_mfma_f32_32x32x16_bf16 v[54:69], v[248:251], v[208:211], v[54:69]
	v_add_f32_e32 v86, v102, v86
	v_add_f32_e32 v86, v87, v86
	s_waitcnt lgkmcnt(6)
	v_mfma_f32_32x32x16_bf16 v[54:69], v[222:225], v[212:215], v[54:69]
	v_add_f32_e32 v86, v88, v86
	v_add_f32_e32 v86, v89, v86
	s_waitcnt lgkmcnt(5)
	v_mfma_f32_32x32x16_bf16 v[38:53], v[216:219], v[208:211], v[38:53]
	v_add_f32_e32 v86, v90, v86
	v_add_f32_e32 v86, v91, v86
	s_waitcnt lgkmcnt(4)
	v_mfma_f32_32x32x16_bf16 v[38:53], v[228:231], v[212:215], v[38:53]
	v_add_f32_e32 v86, v92, v86
	v_add_f32_e32 v86, v93, v86
	s_waitcnt lgkmcnt(3)
	v_mfma_f32_32x32x16_bf16 v[22:37], v[232:235], v[208:211], v[22:37]
	v_add_f32_e32 v86, v94, v86
	v_add_f32_e32 v86, v95, v86
	s_waitcnt lgkmcnt(2)
	v_mfma_f32_32x32x16_bf16 v[22:37], v[236:239], v[212:215], v[22:37]
	v_add_f32_e32 v86, v96, v86
	v_add_f32_e32 v86, v97, v86
	s_waitcnt lgkmcnt(1)
	v_mfma_f32_32x32x16_bf16 v[6:21], v[240:243], v[208:211], v[6:21]
	v_add_f32_e32 v86, v98, v86
	v_add_f32_e32 v86, v99, v86
	s_waitcnt lgkmcnt(0)
	v_mfma_f32_32x32x16_bf16 v[6:21], v[244:247], v[212:215], v[6:21]
	v_add_f32_e32 v86, v100, v86
	v_add_f32_e32 v194, v101, v86
	s_setprio 0
	s_add_i32 s7, s5, -2
	s_cmp_lt_u32 s7, s4
	s_cselect_b64 s[2:3], -1, 0
	s_cmp_ge_u32 s7, s4
	s_cbranch_scc1 .LBB0_1306
	s_mov_b32 s7, 0xd400
	v_add3_u32 v208, v195, v197, s7
	s_waitcnt vmcnt(3)
	ds_write_b128 v196, v[162:165] offset:36864
	s_waitcnt vmcnt(1)
	ds_write2_b64 v208, v[170:171], v[172:173] offset1:1
	ds_write_b128 v199, v[166:169] offset:36864
	v_add3_u32 v208, v195, v200, s7
	s_waitcnt vmcnt(0)
	ds_write2_b64 v208, v[174:175], v[176:177] offset1:1
.LBB0_1306:
	s_andn2_b64 vcc, exec, s[2:3]
	s_mov_b64 s[2:3], -1
	s_waitcnt lgkmcnt(0)
	s_barrier
	s_cbranch_vccnz .LBB0_1311
	s_cmp_ge_u32 s5, s4
	s_cbranch_scc1 .LBB0_1309
	v_lshl_add_u64 v[86:87], v[192:193], 0, s[18:19]
	v_add_co_u32_e32 v86, vcc, 0xc000, v86
	s_nop 1
	v_addc_co_u32_e32 v87, vcc, 0, v87, vcc
	global_load_dwordx4 v[162:165], v[86:87], off
	v_lshl_add_u64 v[86:87], v[190:191], 0, s[18:19]
	v_add_co_u32_e32 v86, vcc, 0xc000, v86
	s_nop 1
	v_addc_co_u32_e32 v87, vcc, 0, v87, vcc
	global_load_dwordx4 v[166:169], v[86:87], off
	v_lshl_add_u64 v[86:87], v[188:189], 0, s[18:19]
	global_load_dwordx4 v[170:173], v[86:87], off offset:384
	v_lshl_add_u64 v[86:87], v[186:187], 0, s[18:19]
	global_load_dwordx4 v[174:177], v[86:87], off offset:384
; #define LAS __attribute__((address_space(3)))
; __device__ __forceinline__ unsigned pk2(float lo, float hi) { f32x2_t v = {lo, hi}; bf16x2_t b = __builtin_convertvector(v, bf16x2_t); return __builtin_bit_cast(unsigned, b); }
; __device__ __forceinline__ void dsa_unit32(const Args& a, LAS unsigned char* lds, const LAS unsigned long long* maskl, int b, int qb, int tid, int wave, int lane) {
;     ...
;     auto compute = [&](int buf, int kt) {
;         const unsigned long long mw = maskl[l31 * 32 + kt];
;         const LAS bf16* Ks = (const LAS bf16*)(lds + buf * STG); const LAS bf16* Vs = (const LAS bf16*)(lds + buf * STG + KBYTES);
;         f32x16 S2[2];
; #pragma unroll
;         for (int kh = 0; kh < 2; ++kh) {
; #pragma unroll
;             for (int i = 0; i < 16; ++i) S2[kh][i] = negB;
;             __builtin_amdgcn_s_setprio(1);
; #pragma unroll
;             for (int ks = 0; ks < 8; ++ks) S2[kh] = mfma32(*(const LAS bf16x8*)(Ks + (32 * kh + l31) * KS + 16 * ks + 8 * hi), qf[ks], S2[kh]);
;             __builtin_amdgcn_s_setprio(0);
;         }
; #pragma unroll
;         for (int kh = 0; kh < 2; ++kh) {
;             const unsigned mh = (unsigned)(mw >> (32 * kh + 4 * hi));
;             float p[16];
; #pragma unroll
;             for (int i = 0; i < 16; ++i) { const float e = __builtin_amdgcn_exp2f(S2[kh][i]);
;                 const int keep = __builtin_amdgcn_sbfe((int)mh, 8 * (i >> 2) + (i & 3), 1);
;                 p[i] = __builtin_bit_cast(float, __builtin_bit_cast(int, e) & keep); l += p[i]; }
;             u32x4 w0, w1;
;             w0.x = pk2(p[0], p[1]); w0.y = pk2(p[2], p[3]); w0.z = pk2(p[4], p[5]); w0.w = pk2(p[6], p[7]);
;             w1.x = pk2(p[8], p[9]); w1.y = pk2(p[10], p[11]); w1.z = pk2(p[12], p[13]); w1.w = pk2(p[14], p[15]);
;             const bf16x8 pa = __builtin_bit_cast(bf16x8, w0), pb = __builtin_bit_cast(bf16x8, w1);
;             __builtin_amdgcn_s_setprio(1);
; #pragma unroll
;             for (int ct = 0; ct < 4; ++ct) {
;                 const LAS bf16* vr = Vs + (32 * ct + l31) * VS + 4 * hi + 32 * kh;
;                 O[ct] = mfma32(cat8(*(const LAS u32x2*)(vr), *(const LAS u32x2*)(vr + 8)), pa, O[ct]);
;                 O[ct] = mfma32(cat8(*(const LAS u32x2*)(vr + 16), *(const LAS u32x2*)(vr + 24)), pb, O[ct]);
;             }
;             __builtin_amdgcn_s_setprio(0);
;         }
.LBB0_1309:
	ds_read_b64 v[220:221], v206
	v_add_u32_e32 v207, v202, v180
	ds_read_b128 v[216:219], v207 offset:36864
	ds_read_b128 v[228:231], v207 offset:36896
	ds_read_b128 v[232:235], v207 offset:36928
	ds_read_b128 v[236:239], v207 offset:36960
	ds_read_b128 v[240:243], v207 offset:36992
	ds_read_b128 v[244:247], v207 offset:37024
	ds_read_b128 v[248:251], v207 offset:37056
	ds_read_b128 v[222:225], v207 offset:37088
	ds_read_b128 v[208:211], v207 offset:45568
	ds_read_b128 v[212:215], v207 offset:45600
	s_setprio 1
	s_waitcnt lgkmcnt(9)
	v_mfma_f32_32x32x16_bf16 v[102:117], v[216:219], v[126:129], v[70:85]
	ds_read_b128 v[216:219], v207 offset:45632
	s_waitcnt lgkmcnt(9)
	v_mfma_f32_32x32x16_bf16 v[102:117], v[228:231], v[0:3], v[102:117]
	ds_read_b128 v[228:231], v207 offset:45664
	s_waitcnt lgkmcnt(9)
	v_mfma_f32_32x32x16_bf16 v[102:117], v[232:235], v[118:121], v[102:117]
	ds_read_b128 v[232:235], v207 offset:45696
	s_waitcnt lgkmcnt(9)
	v_mfma_f32_32x32x16_bf16 v[102:117], v[236:239], v[122:125], v[102:117]
	ds_read_b128 v[236:239], v207 offset:45728
	s_waitcnt lgkmcnt(9)
	v_mfma_f32_32x32x16_bf16 v[102:117], v[240:243], v[130:133], v[102:117]
	ds_read_b128 v[240:243], v207 offset:45760
	s_waitcnt lgkmcnt(9)
	v_mfma_f32_32x32x16_bf16 v[102:117], v[244:247], v[134:137], v[102:117]
	ds_read_b128 v[244:247], v207 offset:45792
	s_waitcnt lgkmcnt(9)
	v_mfma_f32_32x32x16_bf16 v[102:117], v[248:251], v[138:141], v[102:117]
	s_waitcnt lgkmcnt(8)
	v_mfma_f32_32x32x16_bf16 v[102:117], v[222:225], v[142:145], v[102:117]
	s_waitcnt lgkmcnt(7)
	v_mfma_f32_32x32x16_bf16 v[86:101], v[208:211], v[126:129], v[70:85]
	s_waitcnt lgkmcnt(6)
	v_mfma_f32_32x32x16_bf16 v[86:101], v[212:215], v[0:3], v[86:101]
	s_waitcnt lgkmcnt(5)
	v_mfma_f32_32x32x16_bf16 v[86:101], v[216:219], v[118:121], v[86:101]
	ds_read2_b64 v[248:251], v204 offset0:0 offset1:2
	ds_read2_b64 v[222:225], v204 offset0:4 offset1:6
	v_add_u32_e32 v207, 4864, v204
	ds_read2_b64 v[216:219], v207 offset0:0 offset1:2
	s_waitcnt lgkmcnt(7)
	v_mfma_f32_32x32x16_bf16 v[86:101], v[228:231], v[122:125], v[86:101]
	ds_read2_b64 v[228:231], v207 offset0:4 offset1:6
	s_waitcnt lgkmcnt(7)
	v_mfma_f32_32x32x16_bf16 v[86:101], v[232:235], v[130:133], v[86:101]
	v_add_u32_e32 v207, 9728, v204
	ds_read2_b64 v[232:235], v207 offset0:0 offset1:2
	s_waitcnt lgkmcnt(7)
	v_mfma_f32_32x32x16_bf16 v[86:101], v[236:239], v[134:137], v[86:101]
	ds_read2_b64 v[236:239], v207 offset0:4 offset1:6
	s_waitcnt lgkmcnt(7)
	v_mfma_f32_32x32x16_bf16 v[86:101], v[240:243], v[138:141], v[86:101]
	v_add_u32_e32 v207, 14592, v204
	ds_read2_b64 v[240:243], v207 offset0:0 offset1:2
	s_waitcnt lgkmcnt(7)
	v_mfma_f32_32x32x16_bf16 v[86:101], v[244:247], v[142:145], v[86:101]
	ds_read2_b64 v[244:247], v207 offset0:4 offset1:6
	s_setprio 0
	v_lshrrev_b64 v[208:209], v182, v[220:221]
	v_exp_f32_e32 v102, v102
	v_bfe_i32 v209, v208, 0, 1
	v_exp_f32_e32 v103, v103
	v_bfe_i32 v210, v208, 1, 1
	v_and_b32_e32 v102, v102, v209
	v_exp_f32_e32 v104, v104
	v_bfe_i32 v211, v208, 2, 1
	v_and_b32_e32 v103, v103, v210
	v_exp_f32_e32 v105, v105
	v_bfe_i32 v209, v208, 3, 1
	v_and_b32_e32 v104, v104, v211
	v_exp_f32_e32 v106, v106
	v_bfe_i32 v210, v208, 8, 1
	v_and_b32_e32 v105, v105, v209
	v_exp_f32_e32 v107, v107
	v_bfe_i32 v211, v208, 9, 1
	v_and_b32_e32 v106, v106, v210
	v_exp_f32_e32 v108, v108
	v_bfe_i32 v209, v208, 10, 1
	v_and_b32_e32 v107, v107, v211
	v_exp_f32_e32 v109, v109
	v_bfe_i32 v210, v208, 11, 1
	v_and_b32_e32 v108, v108, v209
	v_exp_f32_e32 v110, v110
	v_bfe_i32 v211, v208, 16, 1
	v_and_b32_e32 v109, v109, v210
	v_exp_f32_e32 v111, v111
	v_bfe_i32 v209, v208, 17, 1
	v_and_b32_e32 v110, v110, v211
	v_exp_f32_e32 v112, v112
	v_bfe_i32 v210, v208, 18, 1
	v_and_b32_e32 v111, v111, v209
	v_exp_f32_e32 v113, v113
	v_bfe_i32 v211, v208, 19, 1
	v_and_b32_e32 v112, v112, v210
	v_exp_f32_e32 v114, v114
	v_bfe_i32 v209, v208, 24, 1
	v_and_b32_e32 v113, v113, v211
	v_exp_f32_e32 v115, v115
	v_bfe_i32 v210, v208, 25, 1
	v_and_b32_e32 v114, v114, v209
	v_exp_f32_e32 v116, v116
	v_bfe_i32 v211, v208, 26, 1
	v_and_b32_e32 v115, v115, v210
	v_exp_f32_e32 v117, v117
	v_bfe_i32 v209, v208, 27, 1
	v_and_b32_e32 v116, v116, v211
	s_nop 0
	v_and_b32_e32 v117, v117, v209
	v_cvt_pk_bf16_f32 v208, v102, v103
	v_cvt_pk_bf16_f32 v209, v104, v105
	v_cvt_pk_bf16_f32 v210, v106, v107
	v_cvt_pk_bf16_f32 v211, v108, v109
	v_cvt_pk_bf16_f32 v212, v110, v111
	v_cvt_pk_bf16_f32 v213, v112, v113
	v_cvt_pk_bf16_f32 v214, v114, v115
	v_cvt_pk_bf16_f32 v215, v116, v117
	s_nop 1
	s_setprio 1
	s_waitcnt lgkmcnt(7)
	v_mfma_f32_32x32x16_bf16 v[54:69], v[248:251], v[208:211], v[54:69]
	ds_read2_b64 v[248:251], v204 offset0:8 offset1:10
	v_add_f32_e32 v102, v194, v102
	v_add_f32_e32 v102, v103, v102
	s_waitcnt lgkmcnt(7)
; #define LAS __attribute__((address_space(3)))
; __device__ __forceinline__ unsigned pk2(float lo, float hi) { f32x2_t v = {lo, hi}; bf16x2_t b = __builtin_convertvector(v, bf16x2_t); return __builtin_bit_cast(unsigned, b); }
; __device__ __forceinline__ f32x16 mfma32(bf16x8 a, bf16x8 b, f32x16 c) { return __builtin_amdgcn_mfma_f32_32x32x16_bf16(a, b, c, 0, 0, 0); }
; __device__ __forceinline__ void dsa_unit32(const Args& a, LAS unsigned char* lds, const LAS unsigned long long* maskl, int b, int qb, int tid, int wave, int lane) {
;     ...
;         for (int kh = 0; kh < 2; ++kh) {
;             const unsigned mh = (unsigned)(mw >> (32 * kh + 4 * hi));
;             float p[16];
; #pragma unroll
;             for (int i = 0; i < 16; ++i) { const float e = __builtin_amdgcn_exp2f(S2[kh][i]);
;                 const int keep = __builtin_amdgcn_sbfe((int)mh, 8 * (i >> 2) + (i & 3), 1);
;                 p[i] = __builtin_bit_cast(float, __builtin_bit_cast(int, e) & keep); l += p[i]; }
;             u32x4 w0, w1;
;             w0.x = pk2(p[0], p[1]); w0.y = pk2(p[2], p[3]); w0.z = pk2(p[4], p[5]); w0.w = pk2(p[6], p[7]);
;             w1.x = pk2(p[8], p[9]); w1.y = pk2(p[10], p[11]); w1.z = pk2(p[12], p[13]); w1.w = pk2(p[14], p[15]);
;             const bf16x8 pa = __builtin_bit_cast(bf16x8, w0), pb = __builtin_bit_cast(bf16x8, w1);
;             __builtin_amdgcn_s_setprio(1);
; #pragma unroll
;             for (int ct = 0; ct < 4; ++ct) {
;                 const LAS bf16* vr = Vs + (32 * ct + l31) * VS + 4 * hi + 32 * kh;
;                 O[ct] = mfma32(cat8(*(const LAS u32x2*)(vr), *(const LAS u32x2*)(vr + 8)), pa, O[ct]);
;                 O[ct] = mfma32(cat8(*(const LAS u32x2*)(vr + 16), *(const LAS u32x2*)(vr + 24)), pb, O[ct]);
;             }
;             __builtin_amdgcn_s_setprio(0);
;         }
;     ...
;         compute(1, kt + 1);
;         if (kt + 2 < nkt) DSA_LSTORE(0, rk0, rv0);
;         __syncthreads();
	v_mfma_f32_32x32x16_bf16 v[54:69], v[222:225], v[212:215], v[54:69]
	ds_read2_b64 v[222:225], v204 offset0:12 offset1:14
	v_add_f32_e32 v102, v104, v102
	v_add_f32_e32 v102, v105, v102
	s_waitcnt lgkmcnt(7)
	v_mfma_f32_32x32x16_bf16 v[38:53], v[216:219], v[208:211], v[38:53]
	v_add_u32_e32 v207, 4864, v204
	ds_read2_b64 v[216:219], v207 offset0:8 offset1:10
	v_add_f32_e32 v102, v106, v102
	v_add_f32_e32 v102, v107, v102
	s_waitcnt lgkmcnt(7)
	v_mfma_f32_32x32x16_bf16 v[38:53], v[228:231], v[212:215], v[38:53]
	ds_read2_b64 v[228:231], v207 offset0:12 offset1:14
	v_add_f32_e32 v102, v108, v102
	v_add_f32_e32 v102, v109, v102
	s_waitcnt lgkmcnt(7)
	v_mfma_f32_32x32x16_bf16 v[22:37], v[232:235], v[208:211], v[22:37]
	v_add_u32_e32 v207, 9728, v204
	ds_read2_b64 v[232:235], v207 offset0:8 offset1:10
	v_add_f32_e32 v102, v110, v102
	v_add_f32_e32 v102, v111, v102
	s_waitcnt lgkmcnt(7)
	v_mfma_f32_32x32x16_bf16 v[22:37], v[236:239], v[212:215], v[22:37]
	ds_read2_b64 v[236:239], v207 offset0:12 offset1:14
	v_add_f32_e32 v102, v112, v102
	v_add_f32_e32 v102, v113, v102
	s_waitcnt lgkmcnt(7)
	v_mfma_f32_32x32x16_bf16 v[6:21], v[240:243], v[208:211], v[6:21]
	v_add_u32_e32 v207, 14592, v204
	ds_read2_b64 v[240:243], v207 offset0:8 offset1:10
	v_add_f32_e32 v102, v114, v102
	v_add_f32_e32 v102, v115, v102
	s_waitcnt lgkmcnt(7)
	v_mfma_f32_32x32x16_bf16 v[6:21], v[244:247], v[212:215], v[6:21]
	ds_read2_b64 v[244:247], v207 offset0:12 offset1:14
	v_add_f32_e32 v102, v116, v102
	v_add_f32_e32 v102, v117, v102
	s_setprio 0
	v_lshrrev_b64 v[208:209], v184, v[220:221]
	v_exp_f32_e32 v86, v86
	v_bfe_i32 v209, v208, 0, 1
	v_exp_f32_e32 v87, v87
	v_bfe_i32 v210, v208, 1, 1
	v_and_b32_e32 v86, v86, v209
	v_exp_f32_e32 v88, v88
	v_bfe_i32 v211, v208, 2, 1
	v_and_b32_e32 v87, v87, v210
	v_exp_f32_e32 v89, v89
	v_bfe_i32 v209, v208, 3, 1
	v_and_b32_e32 v88, v88, v211
	v_exp_f32_e32 v90, v90
	v_bfe_i32 v210, v208, 8, 1
	v_and_b32_e32 v89, v89, v209
	v_exp_f32_e32 v91, v91
	v_bfe_i32 v211, v208, 9, 1
	v_and_b32_e32 v90, v90, v210
	v_exp_f32_e32 v92, v92
	v_bfe_i32 v209, v208, 10, 1
	v_and_b32_e32 v91, v91, v211
	v_exp_f32_e32 v93, v93
	v_bfe_i32 v210, v208, 11, 1
	v_and_b32_e32 v92, v92, v209
	v_exp_f32_e32 v94, v94
	v_bfe_i32 v211, v208, 16, 1
	v_and_b32_e32 v93, v93, v210
	v_exp_f32_e32 v95, v95
	v_bfe_i32 v209, v208, 17, 1
	v_and_b32_e32 v94, v94, v211
	v_exp_f32_e32 v96, v96
	v_bfe_i32 v210, v208, 18, 1
	v_and_b32_e32 v95, v95, v209
	v_exp_f32_e32 v97, v97
	v_bfe_i32 v211, v208, 19, 1
	v_and_b32_e32 v96, v96, v210
	v_exp_f32_e32 v98, v98
	v_bfe_i32 v209, v208, 24, 1
	v_and_b32_e32 v97, v97, v211
	v_exp_f32_e32 v99, v99
	v_bfe_i32 v210, v208, 25, 1
	v_and_b32_e32 v98, v98, v209
	v_exp_f32_e32 v100, v100
	v_bfe_i32 v211, v208, 26, 1
	v_and_b32_e32 v99, v99, v210
	v_exp_f32_e32 v101, v101
	v_bfe_i32 v209, v208, 27, 1
	v_and_b32_e32 v100, v100, v211
	s_nop 0
	v_and_b32_e32 v101, v101, v209
	v_cvt_pk_bf16_f32 v208, v86, v87
	v_cvt_pk_bf16_f32 v209, v88, v89
	v_cvt_pk_bf16_f32 v210, v90, v91
	v_cvt_pk_bf16_f32 v211, v92, v93
	v_cvt_pk_bf16_f32 v212, v94, v95
	v_cvt_pk_bf16_f32 v213, v96, v97
	v_cvt_pk_bf16_f32 v214, v98, v99
	v_cvt_pk_bf16_f32 v215, v100, v101
	s_nop 1
	s_setprio 1
	s_waitcnt lgkmcnt(7)
	v_mfma_f32_32x32x16_bf16 v[54:69], v[248:251], v[208:211], v[54:69]
	v_add_f32_e32 v86, v102, v86
	v_add_f32_e32 v86, v87, v86
	s_waitcnt lgkmcnt(6)
	v_mfma_f32_32x32x16_bf16 v[54:69], v[222:225], v[212:215], v[54:69]
	v_add_f32_e32 v86, v88, v86
	v_add_f32_e32 v86, v89, v86
	s_waitcnt lgkmcnt(5)
	v_mfma_f32_32x32x16_bf16 v[38:53], v[216:219], v[208:211], v[38:53]
	v_add_f32_e32 v86, v90, v86
	v_add_f32_e32 v86, v91, v86
	s_waitcnt lgkmcnt(4)
	v_mfma_f32_32x32x16_bf16 v[38:53], v[228:231], v[212:215], v[38:53]
	v_add_f32_e32 v86, v92, v86
	v_add_f32_e32 v86, v93, v86
	s_waitcnt lgkmcnt(3)
	v_mfma_f32_32x32x16_bf16 v[22:37], v[232:235], v[208:211], v[22:37]
	v_add_f32_e32 v86, v94, v86
	v_add_f32_e32 v86, v95, v86
	s_waitcnt lgkmcnt(2)
	v_mfma_f32_32x32x16_bf16 v[22:37], v[236:239], v[212:215], v[22:37]
	v_add_f32_e32 v86, v96, v86
	v_add_f32_e32 v86, v97, v86
	s_waitcnt lgkmcnt(1)
	v_mfma_f32_32x32x16_bf16 v[6:21], v[240:243], v[208:211], v[6:21]
	v_add_f32_e32 v86, v98, v86
	v_add_f32_e32 v86, v99, v86
	s_waitcnt lgkmcnt(0)
	v_mfma_f32_32x32x16_bf16 v[6:21], v[244:247], v[212:215], v[6:21]
	v_add_f32_e32 v86, v100, v86
	v_add_f32_e32 v194, v101, v86
	s_setprio 0
	s_andn2_b64 vcc, exec, s[0:1]
	s_cbranch_vccnz .LBB0_1301
	s_waitcnt vmcnt(3)
	ds_write_b128 v196, v[146:149]
	s_waitcnt vmcnt(1)
	ds_write2_b64 v198, v[154:155], v[156:157] offset1:1
	ds_write_b128 v199, v[150:153]
	s_waitcnt vmcnt(0)
	ds_write2_b64 v201, v[158:159], v[160:161] offset1:1
	s_branch .LBB0_1301
